# MFMA segments of the six GEMM K-loops: drop the mid-segment setprio 0/1 flip and the already-satisfied lgkmcnt(0) after the barrier
# speedup vs baseline: 1.0169x; 1.0169x over previous
; #define PG8_STAGE(bufoff, gbase, voff) do { _Pragma("unroll") for (int _i = 0; _i < 2; ++_i) \
;         __builtin_amdgcn_global_load_lds((const unsigned*)((const char*)(gbase) + (voff)[_i]), (PG8_LAS unsigned*)(lds + (bufoff) + ldsw + _i * 8192), 16, 0, 0); } while (0)
; #define PG8_LDA(dst, b, h) do { _Pragma("unroll") for (int m = 0; m < 4; ++m) _Pragma("unroll") for (int k = 0; k < 2; ++k) dst[m][k] = *(const PG8_LAS bf16x8*)(lds + PG8_SA(b, h) + aoff + m * 2048 + k * 1024); } while (0)
; #define PG8_LDB(dst, b, h) do { _Pragma("unroll") for (int n = 0; n < 2; ++n) _Pragma("unroll") for (int k = 0; k < 2; ++k) dst[n][k] = *(const PG8_LAS bf16x8*)(lds + PG8_SB(b, h) + boff + n * 2048 + k * 1024); } while (0)
; #define PG8_MMA(ai, bj, At, Bt) do { __builtin_amdgcn_s_setprio(1); _Pragma("unroll") for (int m = 0; m < 4; ++m) _Pragma("unroll") for (int n = 0; n < 2; ++n) _Pragma("unroll") for (int k = 0; k < 2; ++k) \
;         acc[ai][bj][m][n] = __builtin_amdgcn_mfma_f32_16x16x32_bf16(Bt[n][k], At[m][k], acc[ai][bj][m][n], 0, 0, 0); __builtin_amdgcn_s_setprio(0); } while (0)
; #define PG8_WAIT_V(n) asm volatile("s_waitcnt vmcnt(" #n ")" ::: "memory")
; #define PG8_WAIT_L(n) asm volatile("s_waitcnt lgkmcnt(" #n ")" ::: "memory")
; template <class Epi, class Sched, bool ALIGN_EPI = false, bool SP2 = false>
; __device__ __forceinline__ void gemm_phase(PG8_LAS unsigned char* lds, const Gemm g, const Sched& S, const Epi& E) {
;     ...
;             const bool last = (t == nt - 2);
;             const char* a1 = cA + (size_t)(t + 1) * kstep;
;             const char* a2 = last ? nA : cA + (size_t)(t + 2) * kstep; const char* b2 = last ? nB : cB + (size_t)(t + 2) * kstep;
;             const char* a3 = a2 + kstep; const char* b3 = b2 + kstep;
;             if (last && has_next) S.a_ready(nxt);
;             if constexpr (SP2) {
;             PG8_LDB(B0, 0, 0); PG8_LDB(B1, 0, 1); PG8_SCHED; PG8_LDA(At, 0, 0); PG8_STAGE(PG8_SA(1, 1), a1 + hstep, voffA);
;             PG8_WAIT_V(8); PG8_WAIT_L(0); PG8_BAR; PG8_MMA(0, 0, At, B0); PG8_MMA(0, 1, At, B1); PG8_BAR; PG8_SCHED;
;             PG8_LDA(At, 0, 1); PG8_STAGE(PG8_SB(0, 0), b2, voffB); PG8_STAGE(PG8_SB(0, 1), b2 + hstep, voffB); PG8_STAGE(PG8_SA(0, 0), a2, voffA);
;             PG8_WAIT_V(8); PG8_WAIT_L(0); PG8_BAR; PG8_MMA(1, 0, At, B0); PG8_MMA(1, 1, At, B1); PG8_BAR; PG8_SCHED;
.LBB0_111:
	s_add_u32 s76, s12, 0xfffc0080
	s_addc_u32 s77, s13, -1
	s_add_i32 s80, 0, 0x10000
	s_cmp_eq_u32 s69, 12
	s_cselect_b32 s79, s11, s77
	s_cselect_b32 s78, s22, s76
	s_cselect_b32 s77, s23, s67
	s_cselect_b32 s76, s40, s41
	s_add_i32 s86, 0, 0x14000
	v_add_u32_e32 v146, s80, v159
	v_add_u32_e32 v182, s86, v159
	ds_read_b128 v[134:137], v146
	ds_read_b128 v[138:141], v146 offset:1024
	ds_read_b128 v[142:145], v146 offset:2048
	ds_read_b128 v[146:149], v146 offset:3072
	ds_read_b128 v[166:169], v182
	ds_read_b128 v[170:173], v182 offset:1024
	ds_read_b128 v[174:177], v182 offset:2048
	ds_read_b128 v[182:185], v182 offset:3072
	v_lshl_add_u64 v[186:187], s[12:13], 0, v[164:165]
	s_add_i32 m0, s37, 0xc000
	ds_read_b128 v[200:203], v180
	ds_read_b128 v[204:207], v180 offset:1024
	ds_read_b128 v[208:211], v180 offset:2048
	ds_read_b128 v[212:215], v180 offset:3072
	ds_read_b128 v[216:219], v180 offset:4096
	ds_read_b128 v[220:223], v180 offset:5120
	ds_read_b128 v[224:227], v180 offset:6144
	ds_read_b128 v[228:231], v180 offset:7168
	global_load_lds_dwordx4 v[186:187], off
	v_lshl_add_u64 v[186:187], s[12:13], 0, v[162:163]
	s_add_i32 m0, s37, 0xe000
	s_nop 0
	global_load_lds_dwordx4 v[186:187], off
	s_waitcnt vmcnt(8)
	s_waitcnt lgkmcnt(0)
	s_barrier
	s_setprio 1
	v_mfma_f32_16x16x32_bf16 v[130:133], v[134:137], v[200:203], v[130:133]
	v_mfma_f32_16x16x32_bf16 v[126:129], v[142:145], v[200:203], v[126:129]
	v_mfma_f32_16x16x32_bf16 v[114:117], v[134:137], v[208:211], v[114:117]
	v_mfma_f32_16x16x32_bf16 v[110:113], v[142:145], v[208:211], v[110:113]
	v_mfma_f32_16x16x32_bf16 v[98:101], v[134:137], v[216:219], v[98:101]
	v_mfma_f32_16x16x32_bf16 v[94:97], v[142:145], v[216:219], v[94:97]
	v_mfma_f32_16x16x32_bf16 v[78:81], v[134:137], v[224:227], v[78:81]
	v_mfma_f32_16x16x32_bf16 v[74:77], v[142:145], v[224:227], v[74:77]
	v_mfma_f32_16x16x32_bf16 v[130:133], v[138:141], v[204:207], v[130:133]
	v_mfma_f32_16x16x32_bf16 v[126:129], v[146:149], v[204:207], v[126:129]
	v_mfma_f32_16x16x32_bf16 v[114:117], v[138:141], v[212:215], v[114:117]
	v_mfma_f32_16x16x32_bf16 v[110:113], v[146:149], v[212:215], v[110:113]
	v_mfma_f32_16x16x32_bf16 v[98:101], v[138:141], v[220:223], v[98:101]
	v_mfma_f32_16x16x32_bf16 v[94:97], v[146:149], v[220:223], v[94:97]
	v_mfma_f32_16x16x32_bf16 v[78:81], v[138:141], v[228:231], v[78:81]
	v_mfma_f32_16x16x32_bf16 v[74:77], v[146:149], v[228:231], v[74:77]
	v_mfma_f32_16x16x32_bf16 v[122:125], v[166:169], v[200:203], v[122:125]
	v_mfma_f32_16x16x32_bf16 v[118:121], v[174:177], v[200:203], v[118:121]
	v_mfma_f32_16x16x32_bf16 v[106:109], v[166:169], v[208:211], v[106:109]
	v_mfma_f32_16x16x32_bf16 v[102:105], v[174:177], v[208:211], v[102:105]
	v_mfma_f32_16x16x32_bf16 v[90:93], v[166:169], v[216:219], v[90:93]
	v_mfma_f32_16x16x32_bf16 v[86:89], v[174:177], v[216:219], v[86:89]
	v_mfma_f32_16x16x32_bf16 v[70:73], v[166:169], v[224:227], v[70:73]
	v_mfma_f32_16x16x32_bf16 v[66:69], v[174:177], v[224:227], v[66:69]
	v_mfma_f32_16x16x32_bf16 v[122:125], v[170:173], v[204:207], v[122:125]
	v_mfma_f32_16x16x32_bf16 v[118:121], v[182:185], v[204:207], v[118:121]
	v_mfma_f32_16x16x32_bf16 v[106:109], v[170:173], v[212:215], v[106:109]
	v_mfma_f32_16x16x32_bf16 v[102:105], v[182:185], v[212:215], v[102:105]
	v_mfma_f32_16x16x32_bf16 v[90:93], v[170:173], v[220:223], v[90:93]
	v_mfma_f32_16x16x32_bf16 v[86:89], v[182:185], v[220:223], v[86:89]
	v_mfma_f32_16x16x32_bf16 v[70:73], v[170:173], v[228:231], v[70:73]
	v_mfma_f32_16x16x32_bf16 v[66:69], v[182:185], v[228:231], v[66:69]
	s_setprio 0
	s_barrier
	s_add_i32 s80, s80, s36
	v_lshl_add_u64 v[186:187], s[76:77], 0, v[152:153]
	s_mov_b32 m0, s80
	ds_read_b128 v[200:203], v180 offset:16384
	ds_read_b128 v[204:207], v180 offset:17408
	ds_read_b128 v[208:211], v180 offset:18432
	ds_read_b128 v[212:215], v180 offset:19456
	ds_read_b128 v[216:219], v180 offset:20480
	ds_read_b128 v[220:223], v180 offset:21504
	ds_read_b128 v[224:227], v180 offset:22528
	ds_read_b128 v[228:231], v180 offset:23552
	global_load_lds_dwordx4 v[186:187], off
	s_add_i32 m0, s80, 0x2000
	s_add_u32 s80, s76, 0x40000
	v_lshl_add_u64 v[232:233], s[76:77], 0, v[156:157]
	s_addc_u32 s81, s77, 0
	s_add_i32 s86, s86, s36
	global_load_lds_dwordx4 v[232:233], off
	v_lshl_add_u64 v[234:235], s[80:81], 0, v[152:153]
	s_mov_b32 m0, s86
	v_lshl_add_u64 v[236:237], s[78:79], 0, v[154:155]
	global_load_lds_dwordx4 v[234:235], off
	v_lshl_add_u64 v[234:235], s[80:81], 0, v[156:157]
	s_add_i32 m0, s86, 0x2000
	s_nop 0
	global_load_lds_dwordx4 v[234:235], off
	v_lshl_add_u64 v[234:235], s[78:79], 0, v[150:151]
	s_mov_b32 m0, s37
	s_nop 0
	global_load_lds_dwordx4 v[234:235], off
	s_mov_b32 m0, s42
	s_nop 0
	global_load_lds_dwordx4 v[236:237], off
	s_waitcnt vmcnt(8)
	s_waitcnt lgkmcnt(0)
	s_barrier
; #define PG8_STAGE(bufoff, gbase, voff) do { _Pragma("unroll") for (int _i = 0; _i < 2; ++_i) \
;         __builtin_amdgcn_global_load_lds((const unsigned*)((const char*)(gbase) + (voff)[_i]), (PG8_LAS unsigned*)(lds + (bufoff) + ldsw + _i * 8192), 16, 0, 0); } while (0)
; #define PG8_LDA(dst, b, h) do { _Pragma("unroll") for (int m = 0; m < 4; ++m) _Pragma("unroll") for (int k = 0; k < 2; ++k) dst[m][k] = *(const PG8_LAS bf16x8*)(lds + PG8_SA(b, h) + aoff + m * 2048 + k * 1024); } while (0)
; #define PG8_LDB(dst, b, h) do { _Pragma("unroll") for (int n = 0; n < 2; ++n) _Pragma("unroll") for (int k = 0; k < 2; ++k) dst[n][k] = *(const PG8_LAS bf16x8*)(lds + PG8_SB(b, h) + boff + n * 2048 + k * 1024); } while (0)
; #define PG8_MMA(ai, bj, At, Bt) do { __builtin_amdgcn_s_setprio(1); _Pragma("unroll") for (int m = 0; m < 4; ++m) _Pragma("unroll") for (int n = 0; n < 2; ++n) _Pragma("unroll") for (int k = 0; k < 2; ++k) \
;         acc[ai][bj][m][n] = __builtin_amdgcn_mfma_f32_16x16x32_bf16(Bt[n][k], At[m][k], acc[ai][bj][m][n], 0, 0, 0); __builtin_amdgcn_s_setprio(0); } while (0)
; #define PG8_WAIT_V(n) asm volatile("s_waitcnt vmcnt(" #n ")" ::: "memory")
; #define PG8_WAIT_L(n) asm volatile("s_waitcnt lgkmcnt(" #n ")" ::: "memory")
; #define PG8_BAR __builtin_amdgcn_s_barrier()
; #define PG8_SCHED __builtin_amdgcn_sched_barrier(0)
; template <class Epi, class Sched, bool ALIGN_EPI = false, bool SP2 = false>
; __device__ __forceinline__ void gemm_phase(PG8_LAS unsigned char* lds, const Gemm g, const Sched& S, const Epi& E) {
;     ...
;             PG8_WAIT_V(8); PG8_WAIT_L(0); PG8_BAR; PG8_MMA(1, 0, At, B0); PG8_MMA(1, 1, At, B1); PG8_BAR; PG8_SCHED;
;             PG8_LDB(B0, 1, 0); PG8_LDB(B1, 1, 1); PG8_SCHED; PG8_LDA(At, 1, 0); PG8_STAGE(PG8_SA(0, 1), a2 + hstep, voffA);
;             PG8_WAIT_V(8); PG8_WAIT_L(0); PG8_BAR; PG8_MMA(0, 0, At, B0); PG8_MMA(0, 1, At, B1); PG8_BAR; PG8_SCHED;
	s_setprio 1
	v_mfma_f32_16x16x32_bf16 v[62:65], v[134:137], v[200:203], v[62:65]
	v_mfma_f32_16x16x32_bf16 v[58:61], v[142:145], v[200:203], v[58:61]
	v_mfma_f32_16x16x32_bf16 v[46:49], v[134:137], v[208:211], v[46:49]
	v_mfma_f32_16x16x32_bf16 v[42:45], v[142:145], v[208:211], v[42:45]
	v_mfma_f32_16x16x32_bf16 v[30:33], v[134:137], v[216:219], v[30:33]
	v_mfma_f32_16x16x32_bf16 v[26:29], v[142:145], v[216:219], v[26:29]
	v_mfma_f32_16x16x32_bf16 v[14:17], v[134:137], v[224:227], v[14:17]
	v_mfma_f32_16x16x32_bf16 v[10:13], v[142:145], v[224:227], v[10:13]
	v_mfma_f32_16x16x32_bf16 v[62:65], v[138:141], v[204:207], v[62:65]
	v_mfma_f32_16x16x32_bf16 v[58:61], v[146:149], v[204:207], v[58:61]
	v_mfma_f32_16x16x32_bf16 v[46:49], v[138:141], v[212:215], v[46:49]
	v_mfma_f32_16x16x32_bf16 v[42:45], v[146:149], v[212:215], v[42:45]
	v_mfma_f32_16x16x32_bf16 v[30:33], v[138:141], v[220:223], v[30:33]
	v_mfma_f32_16x16x32_bf16 v[26:29], v[146:149], v[220:223], v[26:29]
	v_mfma_f32_16x16x32_bf16 v[14:17], v[138:141], v[228:231], v[14:17]
	v_mfma_f32_16x16x32_bf16 v[10:13], v[146:149], v[228:231], v[10:13]
	v_mfma_f32_16x16x32_bf16 v[54:57], v[166:169], v[200:203], v[54:57]
	v_mfma_f32_16x16x32_bf16 v[50:53], v[174:177], v[200:203], v[50:53]
	v_mfma_f32_16x16x32_bf16 v[38:41], v[166:169], v[208:211], v[38:41]
	v_mfma_f32_16x16x32_bf16 v[34:37], v[174:177], v[208:211], v[34:37]
	v_mfma_f32_16x16x32_bf16 v[22:25], v[166:169], v[216:219], v[22:25]
	v_mfma_f32_16x16x32_bf16 v[18:21], v[174:177], v[216:219], v[18:21]
	v_mfma_f32_16x16x32_bf16 v[6:9], v[166:169], v[224:227], v[6:9]
	v_mfma_f32_16x16x32_bf16 v[2:5], v[174:177], v[224:227], v[2:5]
	v_mfma_f32_16x16x32_bf16 v[54:57], v[170:173], v[204:207], v[54:57]
	v_mfma_f32_16x16x32_bf16 v[50:53], v[182:185], v[204:207], v[50:53]
	v_mfma_f32_16x16x32_bf16 v[38:41], v[170:173], v[212:215], v[38:41]
	v_mfma_f32_16x16x32_bf16 v[34:37], v[182:185], v[212:215], v[34:37]
	v_mfma_f32_16x16x32_bf16 v[22:25], v[170:173], v[220:223], v[22:25]
	v_mfma_f32_16x16x32_bf16 v[18:21], v[182:185], v[220:223], v[18:21]
	v_mfma_f32_16x16x32_bf16 v[6:9], v[170:173], v[228:231], v[6:9]
	v_mfma_f32_16x16x32_bf16 v[2:5], v[182:185], v[228:231], v[2:5]
	s_setprio 0
	s_barrier
	s_add_i32 s80, 0, 0x18000
	s_add_i32 s81, 0, 0x1c000
	v_add_u32_e32 v146, s80, v159
	v_add_u32_e32 v182, s81, v159
	ds_read_b128 v[134:137], v146
	ds_read_b128 v[138:141], v146 offset:1024
	ds_read_b128 v[142:145], v146 offset:2048
	ds_read_b128 v[146:149], v146 offset:3072
	ds_read_b128 v[166:169], v182
	ds_read_b128 v[170:173], v182 offset:1024
	ds_read_b128 v[174:177], v182 offset:2048
	ds_read_b128 v[182:185], v182 offset:3072
	s_add_u32 s78, s78, 0x40000
	s_addc_u32 s79, s79, 0
	s_mov_b32 m0, s48
	v_lshl_add_u64 v[238:239], s[78:79], 0, v[150:151]
	ds_read_b128 v[200:203], v180 offset:32768
	ds_read_b128 v[204:207], v180 offset:33792
	ds_read_b128 v[208:211], v180 offset:34816
	ds_read_b128 v[212:215], v180 offset:35840
	ds_read_b128 v[216:219], v180 offset:36864
	ds_read_b128 v[220:223], v180 offset:37888
	ds_read_b128 v[224:227], v180 offset:38912
	ds_read_b128 v[228:231], v180 offset:39936
	global_load_lds_dwordx4 v[238:239], off
	v_lshl_add_u64 v[238:239], s[78:79], 0, v[154:155]
	s_mov_b32 m0, s49
	s_nop 0
	global_load_lds_dwordx4 v[238:239], off
	s_waitcnt vmcnt(8)
	s_waitcnt lgkmcnt(0)
	s_barrier
	s_setprio 1
	v_mfma_f32_16x16x32_bf16 v[130:133], v[134:137], v[200:203], v[130:133]
	v_mfma_f32_16x16x32_bf16 v[126:129], v[142:145], v[200:203], v[126:129]
	v_mfma_f32_16x16x32_bf16 v[114:117], v[134:137], v[208:211], v[114:117]
	v_mfma_f32_16x16x32_bf16 v[110:113], v[142:145], v[208:211], v[110:113]
	v_mfma_f32_16x16x32_bf16 v[98:101], v[134:137], v[216:219], v[98:101]
	v_mfma_f32_16x16x32_bf16 v[94:97], v[142:145], v[216:219], v[94:97]
	v_mfma_f32_16x16x32_bf16 v[78:81], v[134:137], v[224:227], v[78:81]
	v_mfma_f32_16x16x32_bf16 v[74:77], v[142:145], v[224:227], v[74:77]
	v_mfma_f32_16x16x32_bf16 v[130:133], v[138:141], v[204:207], v[130:133]
	v_mfma_f32_16x16x32_bf16 v[126:129], v[146:149], v[204:207], v[126:129]
	v_mfma_f32_16x16x32_bf16 v[114:117], v[138:141], v[212:215], v[114:117]
	v_mfma_f32_16x16x32_bf16 v[110:113], v[146:149], v[212:215], v[110:113]
	v_mfma_f32_16x16x32_bf16 v[98:101], v[138:141], v[220:223], v[98:101]
	v_mfma_f32_16x16x32_bf16 v[94:97], v[146:149], v[220:223], v[94:97]
	v_mfma_f32_16x16x32_bf16 v[78:81], v[138:141], v[228:231], v[78:81]
	v_mfma_f32_16x16x32_bf16 v[74:77], v[146:149], v[228:231], v[74:77]
	v_mfma_f32_16x16x32_bf16 v[122:125], v[166:169], v[200:203], v[122:125]
	v_mfma_f32_16x16x32_bf16 v[118:121], v[174:177], v[200:203], v[118:121]
	v_mfma_f32_16x16x32_bf16 v[106:109], v[166:169], v[208:211], v[106:109]
	v_mfma_f32_16x16x32_bf16 v[102:105], v[174:177], v[208:211], v[102:105]
	v_mfma_f32_16x16x32_bf16 v[90:93], v[166:169], v[216:219], v[90:93]
	v_mfma_f32_16x16x32_bf16 v[86:89], v[174:177], v[216:219], v[86:89]
	v_mfma_f32_16x16x32_bf16 v[70:73], v[166:169], v[224:227], v[70:73]
	v_mfma_f32_16x16x32_bf16 v[66:69], v[174:177], v[224:227], v[66:69]
	v_mfma_f32_16x16x32_bf16 v[122:125], v[170:173], v[204:207], v[122:125]
	v_mfma_f32_16x16x32_bf16 v[118:121], v[182:185], v[204:207], v[118:121]
	v_mfma_f32_16x16x32_bf16 v[106:109], v[170:173], v[212:215], v[106:109]
	v_mfma_f32_16x16x32_bf16 v[102:105], v[182:185], v[212:215], v[102:105]
	v_mfma_f32_16x16x32_bf16 v[90:93], v[170:173], v[220:223], v[90:93]
	v_mfma_f32_16x16x32_bf16 v[86:89], v[182:185], v[220:223], v[86:89]
	v_mfma_f32_16x16x32_bf16 v[70:73], v[170:173], v[228:231], v[70:73]
	v_mfma_f32_16x16x32_bf16 v[66:69], v[182:185], v[228:231], v[66:69]
	s_setprio 0
	s_barrier
; #define PG8_STAGE(bufoff, gbase, voff) do { _Pragma("unroll") for (int _i = 0; _i < 2; ++_i) \
;         __builtin_amdgcn_global_load_lds((const unsigned*)((const char*)(gbase) + (voff)[_i]), (PG8_LAS unsigned*)(lds + (bufoff) + ldsw + _i * 8192), 16, 0, 0); } while (0)
; #define PG8_LDA(dst, b, h) do { _Pragma("unroll") for (int m = 0; m < 4; ++m) _Pragma("unroll") for (int k = 0; k < 2; ++k) dst[m][k] = *(const PG8_LAS bf16x8*)(lds + PG8_SA(b, h) + aoff + m * 2048 + k * 1024); } while (0)
; #define PG8_MMA(ai, bj, At, Bt) do { __builtin_amdgcn_s_setprio(1); _Pragma("unroll") for (int m = 0; m < 4; ++m) _Pragma("unroll") for (int n = 0; n < 2; ++n) _Pragma("unroll") for (int k = 0; k < 2; ++k) \
;         acc[ai][bj][m][n] = __builtin_amdgcn_mfma_f32_16x16x32_bf16(Bt[n][k], At[m][k], acc[ai][bj][m][n], 0, 0, 0); __builtin_amdgcn_s_setprio(0); } while (0)
; #define PG8_WAIT_V(n) asm volatile("s_waitcnt vmcnt(" #n ")" ::: "memory")
; #define PG8_WAIT_L(n) asm volatile("s_waitcnt lgkmcnt(" #n ")" ::: "memory")
; #define PG8_BAR __builtin_amdgcn_s_barrier()
; #define PG8_SCHED __builtin_amdgcn_sched_barrier(0)
; template <class Epi, class Sched, bool ALIGN_EPI = false, bool SP2 = false>
; __device__ __forceinline__ void gemm_phase(PG8_LAS unsigned char* lds, const Gemm g, const Sched& S, const Epi& E) {
;     ...
;         for (int t = 0; t < nt; t += 2) {
;             const bool last = (t == nt - 2);
;     ...
;             PG8_LDA(At, 1, 1); PG8_STAGE(PG8_SB(1, 0), b3, voffB); PG8_STAGE(PG8_SB(1, 1), b3 + hstep, voffB); PG8_STAGE(PG8_SA(1, 0), a3, voffA);
;             PG8_WAIT_V(8); PG8_WAIT_L(0); PG8_BAR; PG8_MMA(1, 0, At, B0); PG8_MMA(1, 1, At, B1); PG8_BAR; PG8_SCHED;
	s_add_i32 s78, s80, s36
	v_lshl_add_u64 v[186:187], v[186:187], 0, s[38:39]
	s_mov_b32 m0, s78
	ds_read_b128 v[200:203], v180 offset:49152
	ds_read_b128 v[204:207], v180 offset:50176
	ds_read_b128 v[208:211], v180 offset:51200
	ds_read_b128 v[212:215], v180 offset:52224
	ds_read_b128 v[216:219], v180 offset:53248
	ds_read_b128 v[220:223], v180 offset:54272
	ds_read_b128 v[224:227], v180 offset:55296
	ds_read_b128 v[228:231], v180 offset:56320
	global_load_lds_dwordx4 v[186:187], off
	s_add_i32 m0, s78, 0x2000
	s_add_u32 s76, s76, 0x40080
	v_lshl_add_u64 v[186:187], v[232:233], 0, s[38:39]
	s_addc_u32 s77, s77, 0
	s_add_i32 s78, s81, s36
	global_load_lds_dwordx4 v[186:187], off
	v_lshl_add_u64 v[186:187], s[76:77], 0, v[152:153]
	s_mov_b32 m0, s78
	s_nop 0
	global_load_lds_dwordx4 v[186:187], off
	v_lshl_add_u64 v[186:187], s[76:77], 0, v[156:157]
	s_add_i32 m0, s78, 0x2000
	s_nop 0
	global_load_lds_dwordx4 v[186:187], off
	v_lshl_add_u64 v[186:187], v[234:235], 0, s[38:39]
	s_mov_b32 m0, s56
	s_nop 0
	global_load_lds_dwordx4 v[186:187], off
	v_lshl_add_u64 v[186:187], v[236:237], 0, s[38:39]
	s_mov_b32 m0, s75
	s_nop 0
	global_load_lds_dwordx4 v[186:187], off
	s_waitcnt vmcnt(8)
	s_waitcnt lgkmcnt(0)
	s_barrier
	s_setprio 1
	v_mfma_f32_16x16x32_bf16 v[62:65], v[134:137], v[200:203], v[62:65]
	v_mfma_f32_16x16x32_bf16 v[58:61], v[142:145], v[200:203], v[58:61]
	v_mfma_f32_16x16x32_bf16 v[46:49], v[134:137], v[208:211], v[46:49]
	v_mfma_f32_16x16x32_bf16 v[42:45], v[142:145], v[208:211], v[42:45]
	v_mfma_f32_16x16x32_bf16 v[30:33], v[134:137], v[216:219], v[30:33]
	v_mfma_f32_16x16x32_bf16 v[26:29], v[142:145], v[216:219], v[26:29]
	v_mfma_f32_16x16x32_bf16 v[14:17], v[134:137], v[224:227], v[14:17]
	v_mfma_f32_16x16x32_bf16 v[10:13], v[142:145], v[224:227], v[10:13]
	v_mfma_f32_16x16x32_bf16 v[62:65], v[138:141], v[204:207], v[62:65]
	v_mfma_f32_16x16x32_bf16 v[58:61], v[146:149], v[204:207], v[58:61]
	v_mfma_f32_16x16x32_bf16 v[46:49], v[138:141], v[212:215], v[46:49]
	v_mfma_f32_16x16x32_bf16 v[42:45], v[146:149], v[212:215], v[42:45]
	v_mfma_f32_16x16x32_bf16 v[30:33], v[138:141], v[220:223], v[30:33]
	v_mfma_f32_16x16x32_bf16 v[26:29], v[146:149], v[220:223], v[26:29]
	v_mfma_f32_16x16x32_bf16 v[14:17], v[138:141], v[228:231], v[14:17]
	v_mfma_f32_16x16x32_bf16 v[10:13], v[146:149], v[228:231], v[10:13]
	v_mfma_f32_16x16x32_bf16 v[54:57], v[166:169], v[200:203], v[54:57]
	v_mfma_f32_16x16x32_bf16 v[50:53], v[174:177], v[200:203], v[50:53]
	v_mfma_f32_16x16x32_bf16 v[38:41], v[166:169], v[208:211], v[38:41]
	v_mfma_f32_16x16x32_bf16 v[34:37], v[174:177], v[208:211], v[34:37]
	v_mfma_f32_16x16x32_bf16 v[22:25], v[166:169], v[216:219], v[22:25]
	v_mfma_f32_16x16x32_bf16 v[18:21], v[174:177], v[216:219], v[18:21]
	v_mfma_f32_16x16x32_bf16 v[6:9], v[166:169], v[224:227], v[6:9]
	v_mfma_f32_16x16x32_bf16 v[2:5], v[174:177], v[224:227], v[2:5]
	v_mfma_f32_16x16x32_bf16 v[54:57], v[170:173], v[204:207], v[54:57]
	v_mfma_f32_16x16x32_bf16 v[50:53], v[182:185], v[204:207], v[50:53]
	v_mfma_f32_16x16x32_bf16 v[38:41], v[170:173], v[212:215], v[38:41]
	v_mfma_f32_16x16x32_bf16 v[34:37], v[182:185], v[212:215], v[34:37]
	v_mfma_f32_16x16x32_bf16 v[22:25], v[170:173], v[220:223], v[22:25]
	v_mfma_f32_16x16x32_bf16 v[18:21], v[182:185], v[220:223], v[18:21]
	v_mfma_f32_16x16x32_bf16 v[6:9], v[170:173], v[228:231], v[6:9]
	v_mfma_f32_16x16x32_bf16 v[2:5], v[182:185], v[228:231], v[2:5]
	s_setprio 0
	s_barrier
	s_add_i32 s69, s69, 2
	s_add_u32 s41, s41, 0x100
	s_addc_u32 s67, s67, 0
	s_add_u32 s12, s12, 0x100
	s_addc_u32 s13, s13, 0
	s_cmp_gt_u32 s69, 13
	s_cbranch_scc0 .LBB0_111
	s_and_b64 vcc, exec, s[64:65]
	s_cbranch_vccz .LBB0_114
	s_barrier

; #define PG8_STAGE(bufoff, gbase, voff) do { _Pragma("unroll") for (int _i = 0; _i < 2; ++_i) \
;         __builtin_amdgcn_global_load_lds((const unsigned*)((const char*)(gbase) + (voff)[_i]), (PG8_LAS unsigned*)(lds + (bufoff) + ldsw + _i * 8192), 16, 0, 0); } while (0)
; #define PG8_LDA(dst, b, h) do { _Pragma("unroll") for (int m = 0; m < 4; ++m) _Pragma("unroll") for (int k = 0; k < 2; ++k) dst[m][k] = *(const PG8_LAS bf16x8*)(lds + PG8_SA(b, h) + aoff + m * 2048 + k * 1024); } while (0)
; #define PG8_LDB(dst, b, h) do { _Pragma("unroll") for (int n = 0; n < 2; ++n) _Pragma("unroll") for (int k = 0; k < 2; ++k) dst[n][k] = *(const PG8_LAS bf16x8*)(lds + PG8_SB(b, h) + boff + n * 2048 + k * 1024); } while (0)
; #define PG8_MMA(ai, bj, At, Bt) do { __builtin_amdgcn_s_setprio(1); _Pragma("unroll") for (int m = 0; m < 4; ++m) _Pragma("unroll") for (int n = 0; n < 2; ++n) _Pragma("unroll") for (int k = 0; k < 2; ++k) \
;         acc[ai][bj][m][n] = __builtin_amdgcn_mfma_f32_16x16x32_bf16(Bt[n][k], At[m][k], acc[ai][bj][m][n], 0, 0, 0); __builtin_amdgcn_s_setprio(0); } while (0)
; #define PG8_WAIT_V(n) asm volatile("s_waitcnt vmcnt(" #n ")" ::: "memory")
; #define PG8_WAIT_L(n) asm volatile("s_waitcnt lgkmcnt(" #n ")" ::: "memory")
; template <class Epi, class Sched, bool ALIGN_EPI = false, bool SP2 = false>
; __device__ __forceinline__ void gemm_phase(PG8_LAS unsigned char* lds, const Gemm g, const Sched& S, const Epi& E) {
;     ...
;             const bool last = (t == nt - 2);
;             const char* a1 = cA + (size_t)(t + 1) * kstep;
;             const char* a2 = last ? nA : cA + (size_t)(t + 2) * kstep; const char* b2 = last ? nB : cB + (size_t)(t + 2) * kstep;
;             const char* a3 = a2 + kstep; const char* b3 = b2 + kstep;
;             if (last && has_next) S.a_ready(nxt);
;             if constexpr (SP2) {
;             PG8_LDB(B0, 0, 0); PG8_LDB(B1, 0, 1); PG8_SCHED; PG8_LDA(At, 0, 0); PG8_STAGE(PG8_SA(1, 1), a1 + hstep, voffA);
;             PG8_WAIT_V(8); PG8_WAIT_L(0); PG8_BAR; PG8_MMA(0, 0, At, B0); PG8_MMA(0, 1, At, B1); PG8_BAR; PG8_SCHED;
;             PG8_LDA(At, 0, 1); PG8_STAGE(PG8_SB(0, 0), b2, voffB); PG8_STAGE(PG8_SB(0, 1), b2 + hstep, voffB); PG8_STAGE(PG8_SA(0, 0), a2, voffA);
;             PG8_WAIT_V(8); PG8_WAIT_L(0); PG8_BAR; PG8_MMA(1, 0, At, B0); PG8_MMA(1, 1, At, B1); PG8_BAR; PG8_SCHED;
.LBB0_684:
	s_add_u32 s24, s20, 0x100
	s_addc_u32 s25, s21, 0
	s_add_i32 s63, 0, 0x10000
	s_cmp_eq_u32 s62, 16
	s_cselect_b32 s59, s7, s25
	s_cselect_b32 s58, s6, s24
	v_add_u32_e32 v150, s63, v152
	s_cselect_b32 s27, s19, s61
	s_cselect_b32 s26, s18, s41
	s_add_i32 s64, 0, 0x14000
	ds_read_b128 v[146:149], v150
	ds_read_b128 v[156:159], v150 offset:1024
	ds_read_b128 v[160:163], v150 offset:2048
	ds_read_b128 v[164:167], v150 offset:3072
	v_add_u32_e32 v150, s64, v152
	ds_read_b128 v[168:171], v150
	ds_read_b128 v[172:175], v150 offset:1024
	ds_read_b128 v[180:183], v150 offset:2048
	ds_read_b128 v[184:187], v150 offset:3072
	v_lshl_add_u64 v[150:151], s[20:21], 0, v[144:145]
	s_add_i32 m0, s42, 0xc000
	ds_read_b128 v[200:203], v154
	ds_read_b128 v[204:207], v154 offset:1024
	ds_read_b128 v[208:211], v154 offset:2048
	ds_read_b128 v[212:215], v154 offset:3072
	ds_read_b128 v[216:219], v154 offset:4096
	ds_read_b128 v[220:223], v154 offset:5120
	ds_read_b128 v[224:227], v154 offset:6144
	ds_read_b128 v[228:231], v154 offset:7168
	global_load_lds_dwordx4 v[150:151], off
	v_lshl_add_u64 v[150:151], s[20:21], 0, v[142:143]
	s_add_i32 m0, s42, 0xe000
	s_nop 0
	global_load_lds_dwordx4 v[150:151], off
	s_waitcnt vmcnt(8)
	s_waitcnt lgkmcnt(0)
	s_barrier
	s_setprio 1
	v_mfma_f32_16x16x32_bf16 v[130:133], v[146:149], v[200:203], v[130:133]
	v_mfma_f32_16x16x32_bf16 v[126:129], v[160:163], v[200:203], v[126:129]
	v_mfma_f32_16x16x32_bf16 v[114:117], v[146:149], v[208:211], v[114:117]
	v_mfma_f32_16x16x32_bf16 v[110:113], v[160:163], v[208:211], v[110:113]
	v_mfma_f32_16x16x32_bf16 v[98:101], v[146:149], v[216:219], v[98:101]
	v_mfma_f32_16x16x32_bf16 v[94:97], v[160:163], v[216:219], v[94:97]
	v_mfma_f32_16x16x32_bf16 v[78:81], v[146:149], v[224:227], v[78:81]
	v_mfma_f32_16x16x32_bf16 v[74:77], v[160:163], v[224:227], v[74:77]
	v_mfma_f32_16x16x32_bf16 v[130:133], v[156:159], v[204:207], v[130:133]
	v_mfma_f32_16x16x32_bf16 v[126:129], v[164:167], v[204:207], v[126:129]
	v_mfma_f32_16x16x32_bf16 v[114:117], v[156:159], v[212:215], v[114:117]
	v_mfma_f32_16x16x32_bf16 v[110:113], v[164:167], v[212:215], v[110:113]
	v_mfma_f32_16x16x32_bf16 v[98:101], v[156:159], v[220:223], v[98:101]
	v_mfma_f32_16x16x32_bf16 v[94:97], v[164:167], v[220:223], v[94:97]
	v_mfma_f32_16x16x32_bf16 v[78:81], v[156:159], v[228:231], v[78:81]
	v_mfma_f32_16x16x32_bf16 v[74:77], v[164:167], v[228:231], v[74:77]
	v_mfma_f32_16x16x32_bf16 v[122:125], v[168:171], v[200:203], v[122:125]
	v_mfma_f32_16x16x32_bf16 v[118:121], v[180:183], v[200:203], v[118:121]
	v_mfma_f32_16x16x32_bf16 v[106:109], v[168:171], v[208:211], v[106:109]
	v_mfma_f32_16x16x32_bf16 v[102:105], v[180:183], v[208:211], v[102:105]
	v_mfma_f32_16x16x32_bf16 v[90:93], v[168:171], v[216:219], v[90:93]
	v_mfma_f32_16x16x32_bf16 v[86:89], v[180:183], v[216:219], v[86:89]
	v_mfma_f32_16x16x32_bf16 v[70:73], v[168:171], v[224:227], v[70:73]
	v_mfma_f32_16x16x32_bf16 v[66:69], v[180:183], v[224:227], v[66:69]
	v_mfma_f32_16x16x32_bf16 v[122:125], v[172:175], v[204:207], v[122:125]
	v_mfma_f32_16x16x32_bf16 v[118:121], v[184:187], v[204:207], v[118:121]
	v_mfma_f32_16x16x32_bf16 v[106:109], v[172:175], v[212:215], v[106:109]
	v_mfma_f32_16x16x32_bf16 v[102:105], v[184:187], v[212:215], v[102:105]
	v_mfma_f32_16x16x32_bf16 v[90:93], v[172:175], v[220:223], v[90:93]
	v_mfma_f32_16x16x32_bf16 v[86:89], v[184:187], v[220:223], v[86:89]
	v_mfma_f32_16x16x32_bf16 v[70:73], v[172:175], v[228:231], v[70:73]
	v_mfma_f32_16x16x32_bf16 v[66:69], v[184:187], v[228:231], v[66:69]
	s_setprio 0
	s_barrier
	s_add_i32 s20, s63, s29
	v_lshl_add_u64 v[150:151], s[26:27], 0, v[138:139]
	s_mov_b32 m0, s20
	ds_read_b128 v[200:203], v154 offset:16384
	ds_read_b128 v[204:207], v154 offset:17408
	ds_read_b128 v[208:211], v154 offset:18432
	ds_read_b128 v[212:215], v154 offset:19456
	ds_read_b128 v[216:219], v154 offset:20480
	ds_read_b128 v[220:223], v154 offset:21504
	ds_read_b128 v[224:227], v154 offset:22528
	ds_read_b128 v[228:231], v154 offset:23552
	global_load_lds_dwordx4 v[150:151], off
	s_add_i32 m0, s20, 0x2000
	s_add_u32 s20, s26, 0x50000
	v_lshl_add_u64 v[176:177], s[26:27], 0, v[134:135]
	s_addc_u32 s21, s27, 0
	s_add_i32 s63, s64, s29
	global_load_lds_dwordx4 v[176:177], off
	v_lshl_add_u64 v[232:233], s[20:21], 0, v[138:139]
	s_mov_b32 m0, s63
	v_lshl_add_u64 v[234:235], s[58:59], 0, v[136:137]
	global_load_lds_dwordx4 v[232:233], off
	v_lshl_add_u64 v[232:233], s[20:21], 0, v[134:135]
	s_add_i32 m0, s63, 0x2000
	s_nop 0
	global_load_lds_dwordx4 v[232:233], off
	v_lshl_add_u64 v[232:233], s[58:59], 0, v[140:141]
	s_mov_b32 m0, s42
	s_nop 0
	global_load_lds_dwordx4 v[232:233], off
	s_mov_b32 m0, s48
	s_nop 0
	global_load_lds_dwordx4 v[234:235], off
	s_waitcnt vmcnt(8)
	s_waitcnt lgkmcnt(0)
	s_barrier
; #define PG8_STAGE(bufoff, gbase, voff) do { _Pragma("unroll") for (int _i = 0; _i < 2; ++_i) \
;         __builtin_amdgcn_global_load_lds((const unsigned*)((const char*)(gbase) + (voff)[_i]), (PG8_LAS unsigned*)(lds + (bufoff) + ldsw + _i * 8192), 16, 0, 0); } while (0)
; #define PG8_LDA(dst, b, h) do { _Pragma("unroll") for (int m = 0; m < 4; ++m) _Pragma("unroll") for (int k = 0; k < 2; ++k) dst[m][k] = *(const PG8_LAS bf16x8*)(lds + PG8_SA(b, h) + aoff + m * 2048 + k * 1024); } while (0)
; #define PG8_LDB(dst, b, h) do { _Pragma("unroll") for (int n = 0; n < 2; ++n) _Pragma("unroll") for (int k = 0; k < 2; ++k) dst[n][k] = *(const PG8_LAS bf16x8*)(lds + PG8_SB(b, h) + boff + n * 2048 + k * 1024); } while (0)
; #define PG8_MMA(ai, bj, At, Bt) do { __builtin_amdgcn_s_setprio(1); _Pragma("unroll") for (int m = 0; m < 4; ++m) _Pragma("unroll") for (int n = 0; n < 2; ++n) _Pragma("unroll") for (int k = 0; k < 2; ++k) \
;         acc[ai][bj][m][n] = __builtin_amdgcn_mfma_f32_16x16x32_bf16(Bt[n][k], At[m][k], acc[ai][bj][m][n], 0, 0, 0); __builtin_amdgcn_s_setprio(0); } while (0)
; #define PG8_WAIT_V(n) asm volatile("s_waitcnt vmcnt(" #n ")" ::: "memory")
; #define PG8_WAIT_L(n) asm volatile("s_waitcnt lgkmcnt(" #n ")" ::: "memory")
; #define PG8_BAR __builtin_amdgcn_s_barrier()
; #define PG8_SCHED __builtin_amdgcn_sched_barrier(0)
; template <class Epi, class Sched, bool ALIGN_EPI = false, bool SP2 = false>
; __device__ __forceinline__ void gemm_phase(PG8_LAS unsigned char* lds, const Gemm g, const Sched& S, const Epi& E) {
;     ...
;             PG8_WAIT_V(8); PG8_WAIT_L(0); PG8_BAR; PG8_MMA(1, 0, At, B0); PG8_MMA(1, 1, At, B1); PG8_BAR; PG8_SCHED;
;             PG8_LDB(B0, 1, 0); PG8_LDB(B1, 1, 1); PG8_SCHED; PG8_LDA(At, 1, 0); PG8_STAGE(PG8_SA(0, 1), a2 + hstep, voffA);
;             PG8_WAIT_V(8); PG8_WAIT_L(0); PG8_BAR; PG8_MMA(0, 0, At, B0); PG8_MMA(0, 1, At, B1); PG8_BAR; PG8_SCHED;
	s_setprio 1
	v_mfma_f32_16x16x32_bf16 v[62:65], v[146:149], v[200:203], v[62:65]
	v_mfma_f32_16x16x32_bf16 v[58:61], v[160:163], v[200:203], v[58:61]
	v_mfma_f32_16x16x32_bf16 v[46:49], v[146:149], v[208:211], v[46:49]
	v_mfma_f32_16x16x32_bf16 v[42:45], v[160:163], v[208:211], v[42:45]
	v_mfma_f32_16x16x32_bf16 v[30:33], v[146:149], v[216:219], v[30:33]
	v_mfma_f32_16x16x32_bf16 v[26:29], v[160:163], v[216:219], v[26:29]
	v_mfma_f32_16x16x32_bf16 v[14:17], v[146:149], v[224:227], v[14:17]
	v_mfma_f32_16x16x32_bf16 v[10:13], v[160:163], v[224:227], v[10:13]
	v_mfma_f32_16x16x32_bf16 v[62:65], v[156:159], v[204:207], v[62:65]
	v_mfma_f32_16x16x32_bf16 v[58:61], v[164:167], v[204:207], v[58:61]
	v_mfma_f32_16x16x32_bf16 v[46:49], v[156:159], v[212:215], v[46:49]
	v_mfma_f32_16x16x32_bf16 v[42:45], v[164:167], v[212:215], v[42:45]
	v_mfma_f32_16x16x32_bf16 v[30:33], v[156:159], v[220:223], v[30:33]
	v_mfma_f32_16x16x32_bf16 v[26:29], v[164:167], v[220:223], v[26:29]
	v_mfma_f32_16x16x32_bf16 v[14:17], v[156:159], v[228:231], v[14:17]
	v_mfma_f32_16x16x32_bf16 v[10:13], v[164:167], v[228:231], v[10:13]
	v_mfma_f32_16x16x32_bf16 v[54:57], v[168:171], v[200:203], v[54:57]
	v_mfma_f32_16x16x32_bf16 v[50:53], v[180:183], v[200:203], v[50:53]
	v_mfma_f32_16x16x32_bf16 v[38:41], v[168:171], v[208:211], v[38:41]
	v_mfma_f32_16x16x32_bf16 v[34:37], v[180:183], v[208:211], v[34:37]
	v_mfma_f32_16x16x32_bf16 v[22:25], v[168:171], v[216:219], v[22:25]
	v_mfma_f32_16x16x32_bf16 v[18:21], v[180:183], v[216:219], v[18:21]
	v_mfma_f32_16x16x32_bf16 v[6:9], v[168:171], v[224:227], v[6:9]
	v_mfma_f32_16x16x32_bf16 v[2:5], v[180:183], v[224:227], v[2:5]
	v_mfma_f32_16x16x32_bf16 v[54:57], v[172:175], v[204:207], v[54:57]
	v_mfma_f32_16x16x32_bf16 v[50:53], v[184:187], v[204:207], v[50:53]
	v_mfma_f32_16x16x32_bf16 v[38:41], v[172:175], v[212:215], v[38:41]
	v_mfma_f32_16x16x32_bf16 v[34:37], v[184:187], v[212:215], v[34:37]
	v_mfma_f32_16x16x32_bf16 v[22:25], v[172:175], v[220:223], v[22:25]
	v_mfma_f32_16x16x32_bf16 v[18:21], v[184:187], v[220:223], v[18:21]
	v_mfma_f32_16x16x32_bf16 v[6:9], v[172:175], v[228:231], v[6:9]
	v_mfma_f32_16x16x32_bf16 v[2:5], v[184:187], v[228:231], v[2:5]
	s_setprio 0
	s_barrier
	s_add_i32 s63, 0, 0x18000
	v_add_u32_e32 v155, s63, v152
	s_add_i32 s64, 0, 0x1c000
	ds_read_b128 v[146:149], v155
	ds_read_b128 v[156:159], v155 offset:1024
	ds_read_b128 v[160:163], v155 offset:2048
	ds_read_b128 v[164:167], v155 offset:3072
	v_add_u32_e32 v155, s64, v152
	ds_read_b128 v[168:171], v155
	ds_read_b128 v[172:175], v155 offset:1024
	ds_read_b128 v[180:183], v155 offset:2048
	ds_read_b128 v[184:187], v155 offset:3072
	s_add_u32 s20, s58, 0x50000
	s_addc_u32 s21, s59, 0
	s_mov_b32 m0, s49
	v_lshl_add_u64 v[236:237], s[20:21], 0, v[140:141]
	ds_read_b128 v[200:203], v154 offset:32768
	ds_read_b128 v[204:207], v154 offset:33792
	ds_read_b128 v[208:211], v154 offset:34816
	ds_read_b128 v[212:215], v154 offset:35840
	ds_read_b128 v[216:219], v154 offset:36864
	ds_read_b128 v[220:223], v154 offset:37888
	ds_read_b128 v[224:227], v154 offset:38912
	ds_read_b128 v[228:231], v154 offset:39936
	global_load_lds_dwordx4 v[236:237], off
	v_lshl_add_u64 v[236:237], s[20:21], 0, v[136:137]
	s_mov_b32 m0, s52
	s_nop 0
	global_load_lds_dwordx4 v[236:237], off
	s_waitcnt vmcnt(8)
	s_waitcnt lgkmcnt(0)
	s_barrier
	s_setprio 1
	v_mfma_f32_16x16x32_bf16 v[130:133], v[146:149], v[200:203], v[130:133]
	v_mfma_f32_16x16x32_bf16 v[126:129], v[160:163], v[200:203], v[126:129]
	v_mfma_f32_16x16x32_bf16 v[114:117], v[146:149], v[208:211], v[114:117]
	v_mfma_f32_16x16x32_bf16 v[110:113], v[160:163], v[208:211], v[110:113]
	v_mfma_f32_16x16x32_bf16 v[98:101], v[146:149], v[216:219], v[98:101]
	v_mfma_f32_16x16x32_bf16 v[94:97], v[160:163], v[216:219], v[94:97]
	v_mfma_f32_16x16x32_bf16 v[78:81], v[146:149], v[224:227], v[78:81]
	v_mfma_f32_16x16x32_bf16 v[74:77], v[160:163], v[224:227], v[74:77]
	v_mfma_f32_16x16x32_bf16 v[130:133], v[156:159], v[204:207], v[130:133]
	v_mfma_f32_16x16x32_bf16 v[126:129], v[164:167], v[204:207], v[126:129]
	v_mfma_f32_16x16x32_bf16 v[114:117], v[156:159], v[212:215], v[114:117]
	v_mfma_f32_16x16x32_bf16 v[110:113], v[164:167], v[212:215], v[110:113]
	v_mfma_f32_16x16x32_bf16 v[98:101], v[156:159], v[220:223], v[98:101]
	v_mfma_f32_16x16x32_bf16 v[94:97], v[164:167], v[220:223], v[94:97]
	v_mfma_f32_16x16x32_bf16 v[78:81], v[156:159], v[228:231], v[78:81]
	v_mfma_f32_16x16x32_bf16 v[74:77], v[164:167], v[228:231], v[74:77]
	v_mfma_f32_16x16x32_bf16 v[122:125], v[168:171], v[200:203], v[122:125]
	v_mfma_f32_16x16x32_bf16 v[118:121], v[180:183], v[200:203], v[118:121]
	v_mfma_f32_16x16x32_bf16 v[106:109], v[168:171], v[208:211], v[106:109]
	v_mfma_f32_16x16x32_bf16 v[102:105], v[180:183], v[208:211], v[102:105]
	v_mfma_f32_16x16x32_bf16 v[90:93], v[168:171], v[216:219], v[90:93]
	v_mfma_f32_16x16x32_bf16 v[86:89], v[180:183], v[216:219], v[86:89]
	v_mfma_f32_16x16x32_bf16 v[70:73], v[168:171], v[224:227], v[70:73]
	v_mfma_f32_16x16x32_bf16 v[66:69], v[180:183], v[224:227], v[66:69]
	v_mfma_f32_16x16x32_bf16 v[122:125], v[172:175], v[204:207], v[122:125]
	v_mfma_f32_16x16x32_bf16 v[118:121], v[184:187], v[204:207], v[118:121]
	v_mfma_f32_16x16x32_bf16 v[106:109], v[172:175], v[212:215], v[106:109]
	v_mfma_f32_16x16x32_bf16 v[102:105], v[184:187], v[212:215], v[102:105]
	v_mfma_f32_16x16x32_bf16 v[90:93], v[172:175], v[220:223], v[90:93]
	v_mfma_f32_16x16x32_bf16 v[86:89], v[184:187], v[220:223], v[86:89]
	v_mfma_f32_16x16x32_bf16 v[70:73], v[172:175], v[228:231], v[70:73]
	v_mfma_f32_16x16x32_bf16 v[66:69], v[184:187], v[228:231], v[66:69]
	s_setprio 0
	s_barrier
; #define PG8_STAGE(bufoff, gbase, voff) do { _Pragma("unroll") for (int _i = 0; _i < 2; ++_i) \
;         __builtin_amdgcn_global_load_lds((const unsigned*)((const char*)(gbase) + (voff)[_i]), (PG8_LAS unsigned*)(lds + (bufoff) + ldsw + _i * 8192), 16, 0, 0); } while (0)
; #define PG8_LDA(dst, b, h) do { _Pragma("unroll") for (int m = 0; m < 4; ++m) _Pragma("unroll") for (int k = 0; k < 2; ++k) dst[m][k] = *(const PG8_LAS bf16x8*)(lds + PG8_SA(b, h) + aoff + m * 2048 + k * 1024); } while (0)
; #define PG8_MMA(ai, bj, At, Bt) do { __builtin_amdgcn_s_setprio(1); _Pragma("unroll") for (int m = 0; m < 4; ++m) _Pragma("unroll") for (int n = 0; n < 2; ++n) _Pragma("unroll") for (int k = 0; k < 2; ++k) \
;         acc[ai][bj][m][n] = __builtin_amdgcn_mfma_f32_16x16x32_bf16(Bt[n][k], At[m][k], acc[ai][bj][m][n], 0, 0, 0); __builtin_amdgcn_s_setprio(0); } while (0)
; #define PG8_WAIT_V(n) asm volatile("s_waitcnt vmcnt(" #n ")" ::: "memory")
; #define PG8_WAIT_L(n) asm volatile("s_waitcnt lgkmcnt(" #n ")" ::: "memory")
; #define PG8_BAR __builtin_amdgcn_s_barrier()
; #define PG8_SCHED __builtin_amdgcn_sched_barrier(0)
; template <class Epi, class Sched, bool ALIGN_EPI = false, bool SP2 = false>
; __device__ __forceinline__ void gemm_phase(PG8_LAS unsigned char* lds, const Gemm g, const Sched& S, const Epi& E) {
;     ...
;         for (int t = 0; t < nt; t += 2) {
;             const bool last = (t == nt - 2);
;             const char* a1 = cA + (size_t)(t + 1) * kstep;
;             const char* a2 = last ? nA : cA + (size_t)(t + 2) * kstep; const char* b2 = last ? nB : cB + (size_t)(t + 2) * kstep;
;     ...
;             PG8_LDA(At, 1, 1); PG8_STAGE(PG8_SB(1, 0), b3, voffB); PG8_STAGE(PG8_SB(1, 1), b3 + hstep, voffB); PG8_STAGE(PG8_SA(1, 0), a3, voffA);
;             PG8_WAIT_V(8); PG8_WAIT_L(0); PG8_BAR; PG8_MMA(1, 0, At, B0); PG8_MMA(1, 1, At, B1); PG8_BAR; PG8_SCHED;
	s_add_i32 s20, s63, s29
	v_lshl_add_u64 v[150:151], v[150:151], 0, s[38:39]
	s_mov_b32 m0, s20
	ds_read_b128 v[200:203], v154 offset:49152
	ds_read_b128 v[204:207], v154 offset:50176
	ds_read_b128 v[208:211], v154 offset:51200
	ds_read_b128 v[212:215], v154 offset:52224
	ds_read_b128 v[216:219], v154 offset:53248
	ds_read_b128 v[220:223], v154 offset:54272
	ds_read_b128 v[224:227], v154 offset:55296
	ds_read_b128 v[228:231], v154 offset:56320
	global_load_lds_dwordx4 v[150:151], off
	s_add_i32 m0, s20, 0x2000
	s_add_u32 s20, s26, 0x50080
	v_lshl_add_u64 v[150:151], v[176:177], 0, s[38:39]
	s_addc_u32 s21, s27, 0
	s_add_i32 s26, s64, s29
	global_load_lds_dwordx4 v[150:151], off
	v_lshl_add_u64 v[150:151], s[20:21], 0, v[138:139]
	s_mov_b32 m0, s26
	s_nop 0
	global_load_lds_dwordx4 v[150:151], off
	v_lshl_add_u64 v[150:151], s[20:21], 0, v[134:135]
	s_add_i32 m0, s26, 0x2000
	s_nop 0
	global_load_lds_dwordx4 v[150:151], off
	v_lshl_add_u64 v[150:151], v[232:233], 0, s[38:39]
	s_mov_b32 m0, s53
	s_nop 0
	global_load_lds_dwordx4 v[150:151], off
	v_lshl_add_u64 v[150:151], v[234:235], 0, s[38:39]
	s_mov_b32 m0, s54
	s_nop 0
	global_load_lds_dwordx4 v[150:151], off
	s_waitcnt vmcnt(8)
	s_waitcnt lgkmcnt(0)
	s_barrier
	s_setprio 1
	v_mfma_f32_16x16x32_bf16 v[62:65], v[146:149], v[200:203], v[62:65]
	v_mfma_f32_16x16x32_bf16 v[58:61], v[160:163], v[200:203], v[58:61]
	v_mfma_f32_16x16x32_bf16 v[46:49], v[146:149], v[208:211], v[46:49]
	v_mfma_f32_16x16x32_bf16 v[42:45], v[160:163], v[208:211], v[42:45]
	v_mfma_f32_16x16x32_bf16 v[30:33], v[146:149], v[216:219], v[30:33]
	v_mfma_f32_16x16x32_bf16 v[26:29], v[160:163], v[216:219], v[26:29]
	v_mfma_f32_16x16x32_bf16 v[14:17], v[146:149], v[224:227], v[14:17]
	v_mfma_f32_16x16x32_bf16 v[10:13], v[160:163], v[224:227], v[10:13]
	v_mfma_f32_16x16x32_bf16 v[62:65], v[156:159], v[204:207], v[62:65]
	v_mfma_f32_16x16x32_bf16 v[58:61], v[164:167], v[204:207], v[58:61]
	v_mfma_f32_16x16x32_bf16 v[46:49], v[156:159], v[212:215], v[46:49]
	v_mfma_f32_16x16x32_bf16 v[42:45], v[164:167], v[212:215], v[42:45]
	v_mfma_f32_16x16x32_bf16 v[30:33], v[156:159], v[220:223], v[30:33]
	v_mfma_f32_16x16x32_bf16 v[26:29], v[164:167], v[220:223], v[26:29]
	v_mfma_f32_16x16x32_bf16 v[14:17], v[156:159], v[228:231], v[14:17]
	v_mfma_f32_16x16x32_bf16 v[10:13], v[164:167], v[228:231], v[10:13]
	v_mfma_f32_16x16x32_bf16 v[54:57], v[168:171], v[200:203], v[54:57]
	v_mfma_f32_16x16x32_bf16 v[50:53], v[180:183], v[200:203], v[50:53]
	v_mfma_f32_16x16x32_bf16 v[38:41], v[168:171], v[208:211], v[38:41]
	v_mfma_f32_16x16x32_bf16 v[34:37], v[180:183], v[208:211], v[34:37]
	v_mfma_f32_16x16x32_bf16 v[22:25], v[168:171], v[216:219], v[22:25]
	v_mfma_f32_16x16x32_bf16 v[18:21], v[180:183], v[216:219], v[18:21]
	v_mfma_f32_16x16x32_bf16 v[6:9], v[168:171], v[224:227], v[6:9]
	v_mfma_f32_16x16x32_bf16 v[2:5], v[180:183], v[224:227], v[2:5]
	v_mfma_f32_16x16x32_bf16 v[54:57], v[172:175], v[204:207], v[54:57]
	v_mfma_f32_16x16x32_bf16 v[50:53], v[184:187], v[204:207], v[50:53]
	v_mfma_f32_16x16x32_bf16 v[38:41], v[172:175], v[212:215], v[38:41]
	v_mfma_f32_16x16x32_bf16 v[34:37], v[184:187], v[212:215], v[34:37]
	v_mfma_f32_16x16x32_bf16 v[22:25], v[172:175], v[220:223], v[22:25]
	v_mfma_f32_16x16x32_bf16 v[18:21], v[184:187], v[220:223], v[18:21]
	v_mfma_f32_16x16x32_bf16 v[6:9], v[172:175], v[228:231], v[6:9]
	v_mfma_f32_16x16x32_bf16 v[2:5], v[184:187], v[228:231], v[2:5]
	s_setprio 0
	s_barrier
	s_add_i32 s62, s62, 2
	s_add_u32 s41, s41, 0x100
	s_addc_u32 s61, s61, 0
	s_cmp_gt_u32 s62, 17
	s_mov_b64 s[20:21], s[24:25]
	s_cbranch_scc0 .LBB0_684
	s_and_b64 vcc, exec, s[16:17]
	s_cbranch_vccz .LBB0_687
	s_barrier

; #define PG8_STAGE(bufoff, gbase, voff) do { _Pragma("unroll") for (int _i = 0; _i < 2; ++_i) \
;         __builtin_amdgcn_global_load_lds((const unsigned*)((const char*)(gbase) + (voff)[_i]), (PG8_LAS unsigned*)(lds + (bufoff) + ldsw + _i * 8192), 16, 0, 0); } while (0)
; #define PG8_LDA(dst, b, h) do { _Pragma("unroll") for (int m = 0; m < 4; ++m) _Pragma("unroll") for (int k = 0; k < 2; ++k) dst[m][k] = *(const PG8_LAS bf16x8*)(lds + PG8_SA(b, h) + aoff + m * 2048 + k * 1024); } while (0)
; #define PG8_LDB(dst, b, h) do { _Pragma("unroll") for (int n = 0; n < 2; ++n) _Pragma("unroll") for (int k = 0; k < 2; ++k) dst[n][k] = *(const PG8_LAS bf16x8*)(lds + PG8_SB(b, h) + boff + n * 2048 + k * 1024); } while (0)
; #define PG8_MMA(ai, bj, At, Bt) do { __builtin_amdgcn_s_setprio(1); _Pragma("unroll") for (int m = 0; m < 4; ++m) _Pragma("unroll") for (int n = 0; n < 2; ++n) _Pragma("unroll") for (int k = 0; k < 2; ++k) \
;         acc[ai][bj][m][n] = __builtin_amdgcn_mfma_f32_16x16x32_bf16(Bt[n][k], At[m][k], acc[ai][bj][m][n], 0, 0, 0); __builtin_amdgcn_s_setprio(0); } while (0)
; #define PG8_WAIT_V(n) asm volatile("s_waitcnt vmcnt(" #n ")" ::: "memory")
; #define PG8_WAIT_L(n) asm volatile("s_waitcnt lgkmcnt(" #n ")" ::: "memory")
; #define PG8_BAR __builtin_amdgcn_s_barrier()
; #define PG8_SCHED __builtin_amdgcn_sched_barrier(0)
; template <class Epi, class Sched, bool ALIGN_EPI = false, bool SP2 = false>
; __device__ __forceinline__ void gemm_phase(PG8_LAS unsigned char* lds, const Gemm g, const Sched& S, const Epi& E) {
;     ...
;             const bool last = (t == nt - 2);
;             const char* a1 = cA + (size_t)(t + 1) * kstep;
;             const char* a2 = last ? nA : cA + (size_t)(t + 2) * kstep; const char* b2 = last ? nB : cB + (size_t)(t + 2) * kstep;
;             const char* a3 = a2 + kstep; const char* b3 = b2 + kstep;
;             if (last && has_next) S.a_ready(nxt);
;             if constexpr (SP2) {
;             PG8_LDB(B0, 0, 0); PG8_LDB(B1, 0, 1); PG8_SCHED; PG8_LDA(At, 0, 0); PG8_STAGE(PG8_SA(1, 1), a1 + hstep, voffA);
;             PG8_WAIT_V(8); PG8_WAIT_L(0); PG8_BAR; PG8_MMA(0, 0, At, B0); PG8_MMA(0, 1, At, B1); PG8_BAR; PG8_SCHED;
;             PG8_LDA(At, 0, 1); PG8_STAGE(PG8_SB(0, 0), b2, voffB); PG8_STAGE(PG8_SB(0, 1), b2 + hstep, voffB); PG8_STAGE(PG8_SA(0, 0), a2, voffA);
.LBB0_700:
	s_add_u32 s59, s60, 0xfffe0080
	s_addc_u32 s62, s61, -1
	s_add_i32 s66, 0, 0x10000
	s_cmp_eq_u32 s56, 4
	s_cselect_b32 s65, s19, s62
	s_cselect_b32 s64, s23, s59
	v_add_u32_e32 v154, s66, v156
	s_cselect_b32 s63, s17, s41
	s_cselect_b32 s62, s27, s40
	s_add_i32 s59, 0, 0x14000
	ds_read_b128 v[146:149], v154
	ds_read_b128 v[150:153], v154 offset:1024
	ds_read_b128 v[160:163], v154 offset:2048
	ds_read_b128 v[164:167], v154 offset:3072
	v_add_u32_e32 v154, s59, v156
	ds_read_b128 v[168:171], v154
	ds_read_b128 v[172:175], v154 offset:1024
	ds_read_b128 v[180:183], v154 offset:2048
	ds_read_b128 v[184:187], v154 offset:3072
	v_lshl_add_u64 v[154:155], s[60:61], 0, v[144:145]
	s_add_i32 m0, s42, 0xc000
	ds_read_b128 v[200:203], v158
	ds_read_b128 v[204:207], v158 offset:1024
	ds_read_b128 v[208:211], v158 offset:2048
	ds_read_b128 v[212:215], v158 offset:3072
	ds_read_b128 v[216:219], v158 offset:4096
	ds_read_b128 v[220:223], v158 offset:5120
	ds_read_b128 v[224:227], v158 offset:6144
	ds_read_b128 v[228:231], v158 offset:7168
	global_load_lds_dwordx4 v[154:155], off
	v_lshl_add_u64 v[154:155], s[60:61], 0, v[142:143]
	s_add_i32 m0, s42, 0xe000
	s_nop 0
	global_load_lds_dwordx4 v[154:155], off
	s_waitcnt vmcnt(8)
	s_waitcnt lgkmcnt(0)
	s_barrier
	s_setprio 1
	v_mfma_f32_16x16x32_bf16 v[130:133], v[146:149], v[200:203], v[130:133]
	v_mfma_f32_16x16x32_bf16 v[126:129], v[160:163], v[200:203], v[126:129]
	v_mfma_f32_16x16x32_bf16 v[114:117], v[146:149], v[208:211], v[114:117]
	v_mfma_f32_16x16x32_bf16 v[110:113], v[160:163], v[208:211], v[110:113]
	v_mfma_f32_16x16x32_bf16 v[98:101], v[146:149], v[216:219], v[98:101]
	v_mfma_f32_16x16x32_bf16 v[94:97], v[160:163], v[216:219], v[94:97]
	v_mfma_f32_16x16x32_bf16 v[78:81], v[146:149], v[224:227], v[78:81]
	v_mfma_f32_16x16x32_bf16 v[74:77], v[160:163], v[224:227], v[74:77]
	v_mfma_f32_16x16x32_bf16 v[130:133], v[150:153], v[204:207], v[130:133]
	v_mfma_f32_16x16x32_bf16 v[126:129], v[164:167], v[204:207], v[126:129]
	v_mfma_f32_16x16x32_bf16 v[114:117], v[150:153], v[212:215], v[114:117]
	v_mfma_f32_16x16x32_bf16 v[110:113], v[164:167], v[212:215], v[110:113]
	v_mfma_f32_16x16x32_bf16 v[98:101], v[150:153], v[220:223], v[98:101]
	v_mfma_f32_16x16x32_bf16 v[94:97], v[164:167], v[220:223], v[94:97]
	v_mfma_f32_16x16x32_bf16 v[78:81], v[150:153], v[228:231], v[78:81]
	v_mfma_f32_16x16x32_bf16 v[74:77], v[164:167], v[228:231], v[74:77]
	v_mfma_f32_16x16x32_bf16 v[122:125], v[168:171], v[200:203], v[122:125]
	v_mfma_f32_16x16x32_bf16 v[118:121], v[180:183], v[200:203], v[118:121]
	v_mfma_f32_16x16x32_bf16 v[106:109], v[168:171], v[208:211], v[106:109]
	v_mfma_f32_16x16x32_bf16 v[102:105], v[180:183], v[208:211], v[102:105]
	v_mfma_f32_16x16x32_bf16 v[90:93], v[168:171], v[216:219], v[90:93]
	v_mfma_f32_16x16x32_bf16 v[86:89], v[180:183], v[216:219], v[86:89]
	v_mfma_f32_16x16x32_bf16 v[70:73], v[168:171], v[224:227], v[70:73]
	v_mfma_f32_16x16x32_bf16 v[66:69], v[180:183], v[224:227], v[66:69]
	v_mfma_f32_16x16x32_bf16 v[122:125], v[172:175], v[204:207], v[122:125]
	v_mfma_f32_16x16x32_bf16 v[118:121], v[184:187], v[204:207], v[118:121]
	v_mfma_f32_16x16x32_bf16 v[106:109], v[172:175], v[212:215], v[106:109]
	v_mfma_f32_16x16x32_bf16 v[102:105], v[184:187], v[212:215], v[102:105]
	v_mfma_f32_16x16x32_bf16 v[90:93], v[172:175], v[220:223], v[90:93]
	v_mfma_f32_16x16x32_bf16 v[86:89], v[184:187], v[220:223], v[86:89]
	v_mfma_f32_16x16x32_bf16 v[70:73], v[172:175], v[228:231], v[70:73]
	v_mfma_f32_16x16x32_bf16 v[66:69], v[184:187], v[228:231], v[66:69]
	s_setprio 0
	s_barrier
	s_add_i32 s66, s66, s29
	v_lshl_add_u64 v[154:155], s[62:63], 0, v[138:139]
	s_mov_b32 m0, s66
	ds_read_b128 v[200:203], v158 offset:16384
	ds_read_b128 v[204:207], v158 offset:17408
	ds_read_b128 v[208:211], v158 offset:18432
	ds_read_b128 v[212:215], v158 offset:19456
	ds_read_b128 v[216:219], v158 offset:20480
	ds_read_b128 v[220:223], v158 offset:21504
	ds_read_b128 v[224:227], v158 offset:22528
	ds_read_b128 v[228:231], v158 offset:23552
	global_load_lds_dwordx4 v[154:155], off
	s_add_i32 m0, s66, 0x2000
	s_add_u32 s66, s62, 0x20000
	v_lshl_add_u64 v[176:177], s[62:63], 0, v[134:135]
	s_addc_u32 s67, s63, 0
	s_add_i32 s59, s59, s29
	global_load_lds_dwordx4 v[176:177], off
	v_lshl_add_u64 v[232:233], s[66:67], 0, v[138:139]
	s_mov_b32 m0, s59
	v_lshl_add_u64 v[234:235], s[64:65], 0, v[136:137]
	global_load_lds_dwordx4 v[232:233], off
	v_lshl_add_u64 v[232:233], s[66:67], 0, v[134:135]
	s_add_i32 m0, s59, 0x2000
	s_nop 0
	global_load_lds_dwordx4 v[232:233], off
	v_lshl_add_u64 v[232:233], s[64:65], 0, v[140:141]
	s_mov_b32 m0, s42
	s_nop 0
	global_load_lds_dwordx4 v[232:233], off
	s_mov_b32 m0, s48
	s_nop 0
	global_load_lds_dwordx4 v[234:235], off
	s_waitcnt vmcnt(8)
	s_waitcnt lgkmcnt(0)
	s_barrier
; #define PG8_STAGE(bufoff, gbase, voff) do { _Pragma("unroll") for (int _i = 0; _i < 2; ++_i) \
;         __builtin_amdgcn_global_load_lds((const unsigned*)((const char*)(gbase) + (voff)[_i]), (PG8_LAS unsigned*)(lds + (bufoff) + ldsw + _i * 8192), 16, 0, 0); } while (0)
; #define PG8_LDA(dst, b, h) do { _Pragma("unroll") for (int m = 0; m < 4; ++m) _Pragma("unroll") for (int k = 0; k < 2; ++k) dst[m][k] = *(const PG8_LAS bf16x8*)(lds + PG8_SA(b, h) + aoff + m * 2048 + k * 1024); } while (0)
; #define PG8_LDB(dst, b, h) do { _Pragma("unroll") for (int n = 0; n < 2; ++n) _Pragma("unroll") for (int k = 0; k < 2; ++k) dst[n][k] = *(const PG8_LAS bf16x8*)(lds + PG8_SB(b, h) + boff + n * 2048 + k * 1024); } while (0)
; #define PG8_MMA(ai, bj, At, Bt) do { __builtin_amdgcn_s_setprio(1); _Pragma("unroll") for (int m = 0; m < 4; ++m) _Pragma("unroll") for (int n = 0; n < 2; ++n) _Pragma("unroll") for (int k = 0; k < 2; ++k) \
;         acc[ai][bj][m][n] = __builtin_amdgcn_mfma_f32_16x16x32_bf16(Bt[n][k], At[m][k], acc[ai][bj][m][n], 0, 0, 0); __builtin_amdgcn_s_setprio(0); } while (0)
; #define PG8_WAIT_V(n) asm volatile("s_waitcnt vmcnt(" #n ")" ::: "memory")
; #define PG8_WAIT_L(n) asm volatile("s_waitcnt lgkmcnt(" #n ")" ::: "memory")
; #define PG8_BAR __builtin_amdgcn_s_barrier()
; #define PG8_SCHED __builtin_amdgcn_sched_barrier(0)
; template <class Epi, class Sched, bool ALIGN_EPI = false, bool SP2 = false>
; __device__ __forceinline__ void gemm_phase(PG8_LAS unsigned char* lds, const Gemm g, const Sched& S, const Epi& E) {
;     ...
;             PG8_WAIT_V(8); PG8_WAIT_L(0); PG8_BAR; PG8_MMA(1, 0, At, B0); PG8_MMA(1, 1, At, B1); PG8_BAR; PG8_SCHED;
;             PG8_LDB(B0, 1, 0); PG8_LDB(B1, 1, 1); PG8_SCHED; PG8_LDA(At, 1, 0); PG8_STAGE(PG8_SA(0, 1), a2 + hstep, voffA);
;             PG8_WAIT_V(8); PG8_WAIT_L(0); PG8_BAR; PG8_MMA(0, 0, At, B0); PG8_MMA(0, 1, At, B1); PG8_BAR; PG8_SCHED;
	s_setprio 1
	v_mfma_f32_16x16x32_bf16 v[62:65], v[146:149], v[200:203], v[62:65]
	v_mfma_f32_16x16x32_bf16 v[58:61], v[160:163], v[200:203], v[58:61]
	v_mfma_f32_16x16x32_bf16 v[46:49], v[146:149], v[208:211], v[46:49]
	v_mfma_f32_16x16x32_bf16 v[42:45], v[160:163], v[208:211], v[42:45]
	v_mfma_f32_16x16x32_bf16 v[30:33], v[146:149], v[216:219], v[30:33]
	v_mfma_f32_16x16x32_bf16 v[26:29], v[160:163], v[216:219], v[26:29]
	v_mfma_f32_16x16x32_bf16 v[14:17], v[146:149], v[224:227], v[14:17]
	v_mfma_f32_16x16x32_bf16 v[10:13], v[160:163], v[224:227], v[10:13]
	v_mfma_f32_16x16x32_bf16 v[62:65], v[150:153], v[204:207], v[62:65]
	v_mfma_f32_16x16x32_bf16 v[58:61], v[164:167], v[204:207], v[58:61]
	v_mfma_f32_16x16x32_bf16 v[46:49], v[150:153], v[212:215], v[46:49]
	v_mfma_f32_16x16x32_bf16 v[42:45], v[164:167], v[212:215], v[42:45]
	v_mfma_f32_16x16x32_bf16 v[30:33], v[150:153], v[220:223], v[30:33]
	v_mfma_f32_16x16x32_bf16 v[26:29], v[164:167], v[220:223], v[26:29]
	v_mfma_f32_16x16x32_bf16 v[14:17], v[150:153], v[228:231], v[14:17]
	v_mfma_f32_16x16x32_bf16 v[10:13], v[164:167], v[228:231], v[10:13]
	v_mfma_f32_16x16x32_bf16 v[54:57], v[168:171], v[200:203], v[54:57]
	v_mfma_f32_16x16x32_bf16 v[50:53], v[180:183], v[200:203], v[50:53]
	v_mfma_f32_16x16x32_bf16 v[38:41], v[168:171], v[208:211], v[38:41]
	v_mfma_f32_16x16x32_bf16 v[34:37], v[180:183], v[208:211], v[34:37]
	v_mfma_f32_16x16x32_bf16 v[22:25], v[168:171], v[216:219], v[22:25]
	v_mfma_f32_16x16x32_bf16 v[18:21], v[180:183], v[216:219], v[18:21]
	v_mfma_f32_16x16x32_bf16 v[6:9], v[168:171], v[224:227], v[6:9]
	v_mfma_f32_16x16x32_bf16 v[2:5], v[180:183], v[224:227], v[2:5]
	v_mfma_f32_16x16x32_bf16 v[54:57], v[172:175], v[204:207], v[54:57]
	v_mfma_f32_16x16x32_bf16 v[50:53], v[184:187], v[204:207], v[50:53]
	v_mfma_f32_16x16x32_bf16 v[38:41], v[172:175], v[212:215], v[38:41]
	v_mfma_f32_16x16x32_bf16 v[34:37], v[184:187], v[212:215], v[34:37]
	v_mfma_f32_16x16x32_bf16 v[22:25], v[172:175], v[220:223], v[22:25]
	v_mfma_f32_16x16x32_bf16 v[18:21], v[184:187], v[220:223], v[18:21]
	v_mfma_f32_16x16x32_bf16 v[6:9], v[172:175], v[228:231], v[6:9]
	v_mfma_f32_16x16x32_bf16 v[2:5], v[184:187], v[228:231], v[2:5]
	s_setprio 0
	s_barrier
	s_add_i32 s59, 0, 0x18000
	v_add_u32_e32 v159, s59, v156
	s_add_i32 s66, 0, 0x1c000
	ds_read_b128 v[146:149], v159
	ds_read_b128 v[150:153], v159 offset:1024
	ds_read_b128 v[160:163], v159 offset:2048
	ds_read_b128 v[164:167], v159 offset:3072
	v_add_u32_e32 v159, s66, v156
	ds_read_b128 v[168:171], v159
	ds_read_b128 v[172:175], v159 offset:1024
	ds_read_b128 v[180:183], v159 offset:2048
	ds_read_b128 v[184:187], v159 offset:3072
	s_add_u32 s64, s64, 0x20000
	s_addc_u32 s65, s65, 0
	s_mov_b32 m0, s49
	v_lshl_add_u64 v[236:237], s[64:65], 0, v[140:141]
	ds_read_b128 v[200:203], v158 offset:32768
	ds_read_b128 v[204:207], v158 offset:33792
	ds_read_b128 v[208:211], v158 offset:34816
	ds_read_b128 v[212:215], v158 offset:35840
	ds_read_b128 v[216:219], v158 offset:36864
	ds_read_b128 v[220:223], v158 offset:37888
	ds_read_b128 v[224:227], v158 offset:38912
	ds_read_b128 v[228:231], v158 offset:39936
	global_load_lds_dwordx4 v[236:237], off
	v_lshl_add_u64 v[236:237], s[64:65], 0, v[136:137]
	s_mov_b32 m0, s52
	s_nop 0
	global_load_lds_dwordx4 v[236:237], off
	s_waitcnt vmcnt(8)
	s_waitcnt lgkmcnt(0)
	s_barrier
	s_setprio 1
	v_mfma_f32_16x16x32_bf16 v[130:133], v[146:149], v[200:203], v[130:133]
	v_mfma_f32_16x16x32_bf16 v[126:129], v[160:163], v[200:203], v[126:129]
	v_mfma_f32_16x16x32_bf16 v[114:117], v[146:149], v[208:211], v[114:117]
	v_mfma_f32_16x16x32_bf16 v[110:113], v[160:163], v[208:211], v[110:113]
	v_mfma_f32_16x16x32_bf16 v[98:101], v[146:149], v[216:219], v[98:101]
	v_mfma_f32_16x16x32_bf16 v[94:97], v[160:163], v[216:219], v[94:97]
	v_mfma_f32_16x16x32_bf16 v[78:81], v[146:149], v[224:227], v[78:81]
	v_mfma_f32_16x16x32_bf16 v[74:77], v[160:163], v[224:227], v[74:77]
	v_mfma_f32_16x16x32_bf16 v[130:133], v[150:153], v[204:207], v[130:133]
	v_mfma_f32_16x16x32_bf16 v[126:129], v[164:167], v[204:207], v[126:129]
	v_mfma_f32_16x16x32_bf16 v[114:117], v[150:153], v[212:215], v[114:117]
	v_mfma_f32_16x16x32_bf16 v[110:113], v[164:167], v[212:215], v[110:113]
	v_mfma_f32_16x16x32_bf16 v[98:101], v[150:153], v[220:223], v[98:101]
	v_mfma_f32_16x16x32_bf16 v[94:97], v[164:167], v[220:223], v[94:97]
	v_mfma_f32_16x16x32_bf16 v[78:81], v[150:153], v[228:231], v[78:81]
	v_mfma_f32_16x16x32_bf16 v[74:77], v[164:167], v[228:231], v[74:77]
	v_mfma_f32_16x16x32_bf16 v[122:125], v[168:171], v[200:203], v[122:125]
	v_mfma_f32_16x16x32_bf16 v[118:121], v[180:183], v[200:203], v[118:121]
	v_mfma_f32_16x16x32_bf16 v[106:109], v[168:171], v[208:211], v[106:109]
	v_mfma_f32_16x16x32_bf16 v[102:105], v[180:183], v[208:211], v[102:105]
	v_mfma_f32_16x16x32_bf16 v[90:93], v[168:171], v[216:219], v[90:93]
	v_mfma_f32_16x16x32_bf16 v[86:89], v[180:183], v[216:219], v[86:89]
	v_mfma_f32_16x16x32_bf16 v[70:73], v[168:171], v[224:227], v[70:73]
	v_mfma_f32_16x16x32_bf16 v[66:69], v[180:183], v[224:227], v[66:69]
	v_mfma_f32_16x16x32_bf16 v[122:125], v[172:175], v[204:207], v[122:125]
	v_mfma_f32_16x16x32_bf16 v[118:121], v[184:187], v[204:207], v[118:121]
	v_mfma_f32_16x16x32_bf16 v[106:109], v[172:175], v[212:215], v[106:109]
	v_mfma_f32_16x16x32_bf16 v[102:105], v[184:187], v[212:215], v[102:105]
	v_mfma_f32_16x16x32_bf16 v[90:93], v[172:175], v[220:223], v[90:93]
	v_mfma_f32_16x16x32_bf16 v[86:89], v[184:187], v[220:223], v[86:89]
	v_mfma_f32_16x16x32_bf16 v[70:73], v[172:175], v[228:231], v[70:73]
	v_mfma_f32_16x16x32_bf16 v[66:69], v[184:187], v[228:231], v[66:69]
	s_setprio 0
	s_barrier
; #define PG8_STAGE(bufoff, gbase, voff) do { _Pragma("unroll") for (int _i = 0; _i < 2; ++_i) \
;         __builtin_amdgcn_global_load_lds((const unsigned*)((const char*)(gbase) + (voff)[_i]), (PG8_LAS unsigned*)(lds + (bufoff) + ldsw + _i * 8192), 16, 0, 0); } while (0)
; #define PG8_LDA(dst, b, h) do { _Pragma("unroll") for (int m = 0; m < 4; ++m) _Pragma("unroll") for (int k = 0; k < 2; ++k) dst[m][k] = *(const PG8_LAS bf16x8*)(lds + PG8_SA(b, h) + aoff + m * 2048 + k * 1024); } while (0)
; #define PG8_MMA(ai, bj, At, Bt) do { __builtin_amdgcn_s_setprio(1); _Pragma("unroll") for (int m = 0; m < 4; ++m) _Pragma("unroll") for (int n = 0; n < 2; ++n) _Pragma("unroll") for (int k = 0; k < 2; ++k) \
;         acc[ai][bj][m][n] = __builtin_amdgcn_mfma_f32_16x16x32_bf16(Bt[n][k], At[m][k], acc[ai][bj][m][n], 0, 0, 0); __builtin_amdgcn_s_setprio(0); } while (0)
; #define PG8_WAIT_V(n) asm volatile("s_waitcnt vmcnt(" #n ")" ::: "memory")
; #define PG8_WAIT_L(n) asm volatile("s_waitcnt lgkmcnt(" #n ")" ::: "memory")
; #define PG8_BAR __builtin_amdgcn_s_barrier()
; #define PG8_SCHED __builtin_amdgcn_sched_barrier(0)
; template <class Epi, class Sched, bool ALIGN_EPI = false, bool SP2 = false>
; __device__ __forceinline__ void gemm_phase(PG8_LAS unsigned char* lds, const Gemm g, const Sched& S, const Epi& E) {
;     ...
;         for (int t = 0; t < nt; t += 2) {
;             const bool last = (t == nt - 2);
;             const char* a1 = cA + (size_t)(t + 1) * kstep;
;             const char* a2 = last ? nA : cA + (size_t)(t + 2) * kstep; const char* b2 = last ? nB : cB + (size_t)(t + 2) * kstep;
;     ...
;             PG8_LDA(At, 1, 1); PG8_STAGE(PG8_SB(1, 0), b3, voffB); PG8_STAGE(PG8_SB(1, 1), b3 + hstep, voffB); PG8_STAGE(PG8_SA(1, 0), a3, voffA);
;             PG8_WAIT_V(8); PG8_WAIT_L(0); PG8_BAR; PG8_MMA(1, 0, At, B0); PG8_MMA(1, 1, At, B1); PG8_BAR; PG8_SCHED;
	s_add_i32 s59, s59, s29
	v_lshl_add_u64 v[154:155], v[154:155], 0, s[38:39]
	s_mov_b32 m0, s59
	ds_read_b128 v[200:203], v158 offset:49152
	ds_read_b128 v[204:207], v158 offset:50176
	ds_read_b128 v[208:211], v158 offset:51200
	ds_read_b128 v[212:215], v158 offset:52224
	ds_read_b128 v[216:219], v158 offset:53248
	ds_read_b128 v[220:223], v158 offset:54272
	ds_read_b128 v[224:227], v158 offset:55296
	ds_read_b128 v[228:231], v158 offset:56320
	global_load_lds_dwordx4 v[154:155], off
	s_add_i32 m0, s59, 0x2000
	s_add_u32 s62, s62, 0x20080
	v_lshl_add_u64 v[154:155], v[176:177], 0, s[38:39]
	s_addc_u32 s63, s63, 0
	s_add_i32 s59, s66, s29
	global_load_lds_dwordx4 v[154:155], off
	v_lshl_add_u64 v[154:155], s[62:63], 0, v[138:139]
	s_mov_b32 m0, s59
	s_nop 0
	global_load_lds_dwordx4 v[154:155], off
	v_lshl_add_u64 v[154:155], s[62:63], 0, v[134:135]
	s_add_i32 m0, s59, 0x2000
	s_nop 0
	global_load_lds_dwordx4 v[154:155], off
	v_lshl_add_u64 v[154:155], v[232:233], 0, s[38:39]
	s_mov_b32 m0, s53
	s_nop 0
	global_load_lds_dwordx4 v[154:155], off
	v_lshl_add_u64 v[154:155], v[234:235], 0, s[38:39]
	s_mov_b32 m0, s54
	s_nop 0
	global_load_lds_dwordx4 v[154:155], off
	s_waitcnt vmcnt(8)
	s_waitcnt lgkmcnt(0)
	s_barrier
	s_setprio 1
	v_mfma_f32_16x16x32_bf16 v[62:65], v[146:149], v[200:203], v[62:65]
	v_mfma_f32_16x16x32_bf16 v[58:61], v[160:163], v[200:203], v[58:61]
	v_mfma_f32_16x16x32_bf16 v[46:49], v[146:149], v[208:211], v[46:49]
	v_mfma_f32_16x16x32_bf16 v[42:45], v[160:163], v[208:211], v[42:45]
	v_mfma_f32_16x16x32_bf16 v[30:33], v[146:149], v[216:219], v[30:33]
	v_mfma_f32_16x16x32_bf16 v[26:29], v[160:163], v[216:219], v[26:29]
	v_mfma_f32_16x16x32_bf16 v[14:17], v[146:149], v[224:227], v[14:17]
	v_mfma_f32_16x16x32_bf16 v[10:13], v[160:163], v[224:227], v[10:13]
	v_mfma_f32_16x16x32_bf16 v[62:65], v[150:153], v[204:207], v[62:65]
	v_mfma_f32_16x16x32_bf16 v[58:61], v[164:167], v[204:207], v[58:61]
	v_mfma_f32_16x16x32_bf16 v[46:49], v[150:153], v[212:215], v[46:49]
	v_mfma_f32_16x16x32_bf16 v[42:45], v[164:167], v[212:215], v[42:45]
	v_mfma_f32_16x16x32_bf16 v[30:33], v[150:153], v[220:223], v[30:33]
	v_mfma_f32_16x16x32_bf16 v[26:29], v[164:167], v[220:223], v[26:29]
	v_mfma_f32_16x16x32_bf16 v[14:17], v[150:153], v[228:231], v[14:17]
	v_mfma_f32_16x16x32_bf16 v[10:13], v[164:167], v[228:231], v[10:13]
	v_mfma_f32_16x16x32_bf16 v[54:57], v[168:171], v[200:203], v[54:57]
	v_mfma_f32_16x16x32_bf16 v[50:53], v[180:183], v[200:203], v[50:53]
	v_mfma_f32_16x16x32_bf16 v[38:41], v[168:171], v[208:211], v[38:41]
	v_mfma_f32_16x16x32_bf16 v[34:37], v[180:183], v[208:211], v[34:37]
	v_mfma_f32_16x16x32_bf16 v[22:25], v[168:171], v[216:219], v[22:25]
	v_mfma_f32_16x16x32_bf16 v[18:21], v[180:183], v[216:219], v[18:21]
	v_mfma_f32_16x16x32_bf16 v[6:9], v[168:171], v[224:227], v[6:9]
	v_mfma_f32_16x16x32_bf16 v[2:5], v[180:183], v[224:227], v[2:5]
	v_mfma_f32_16x16x32_bf16 v[54:57], v[172:175], v[204:207], v[54:57]
	v_mfma_f32_16x16x32_bf16 v[50:53], v[184:187], v[204:207], v[50:53]
	v_mfma_f32_16x16x32_bf16 v[38:41], v[172:175], v[212:215], v[38:41]
	v_mfma_f32_16x16x32_bf16 v[34:37], v[184:187], v[212:215], v[34:37]
	v_mfma_f32_16x16x32_bf16 v[22:25], v[172:175], v[220:223], v[22:25]
	v_mfma_f32_16x16x32_bf16 v[18:21], v[184:187], v[220:223], v[18:21]
	v_mfma_f32_16x16x32_bf16 v[6:9], v[172:175], v[228:231], v[6:9]
	v_mfma_f32_16x16x32_bf16 v[2:5], v[184:187], v[228:231], v[2:5]
	s_setprio 0
	s_barrier
	s_add_i32 s56, s56, 2
	s_add_u32 s40, s40, 0x100
	s_addc_u32 s41, s41, 0
	s_add_u32 s60, s60, 0x100
	s_addc_u32 s61, s61, 0
	s_cmp_gt_u32 s56, 5
	s_cbranch_scc0 .LBB0_700
	s_and_b64 vcc, exec, s[14:15]
	s_cbranch_vccz .LBB0_703
	s_barrier

; #define PG8_STAGE(bufoff, gbase, voff) do { _Pragma("unroll") for (int _i = 0; _i < 2; ++_i) \
;         __builtin_amdgcn_global_load_lds((const unsigned*)((const char*)(gbase) + (voff)[_i]), (PG8_LAS unsigned*)(lds + (bufoff) + ldsw + _i * 8192), 16, 0, 0); } while (0)
; #define PG8_LDA(dst, b, h) do { _Pragma("unroll") for (int m = 0; m < 4; ++m) _Pragma("unroll") for (int k = 0; k < 2; ++k) dst[m][k] = *(const PG8_LAS bf16x8*)(lds + PG8_SA(b, h) + aoff + m * 2048 + k * 1024); } while (0)
; #define PG8_LDB(dst, b, h) do { _Pragma("unroll") for (int n = 0; n < 2; ++n) _Pragma("unroll") for (int k = 0; k < 2; ++k) dst[n][k] = *(const PG8_LAS bf16x8*)(lds + PG8_SB(b, h) + boff + n * 2048 + k * 1024); } while (0)
; #define PG8_MMA(ai, bj, At, Bt) do { __builtin_amdgcn_s_setprio(1); _Pragma("unroll") for (int m = 0; m < 4; ++m) _Pragma("unroll") for (int n = 0; n < 2; ++n) _Pragma("unroll") for (int k = 0; k < 2; ++k) \
;         acc[ai][bj][m][n] = __builtin_amdgcn_mfma_f32_16x16x32_bf16(Bt[n][k], At[m][k], acc[ai][bj][m][n], 0, 0, 0); __builtin_amdgcn_s_setprio(0); } while (0)
; #define PG8_WAIT_V(n) asm volatile("s_waitcnt vmcnt(" #n ")" ::: "memory")
; #define PG8_WAIT_L(n) asm volatile("s_waitcnt lgkmcnt(" #n ")" ::: "memory")
; #define PG8_BAR __builtin_amdgcn_s_barrier()
; #define PG8_SCHED __builtin_amdgcn_sched_barrier(0)
; template <class Epi, class Sched, bool ALIGN_EPI = false, bool SP2 = false>
; __device__ __forceinline__ void gemm_phase(PG8_LAS unsigned char* lds, const Gemm g, const Sched& S, const Epi& E) {
;     ...
;             const bool last = (t == nt - 2);
;             const char* a1 = cA + (size_t)(t + 1) * kstep;
;             const char* a2 = last ? nA : cA + (size_t)(t + 2) * kstep; const char* b2 = last ? nB : cB + (size_t)(t + 2) * kstep;
;             const char* a3 = a2 + kstep; const char* b3 = b2 + kstep;
;             if (last && has_next) S.a_ready(nxt);
;             if constexpr (SP2) {
;             PG8_LDB(B0, 0, 0); PG8_LDB(B1, 0, 1); PG8_SCHED; PG8_LDA(At, 0, 0); PG8_STAGE(PG8_SA(1, 1), a1 + hstep, voffA);
;             PG8_WAIT_V(8); PG8_WAIT_L(0); PG8_BAR; PG8_MMA(0, 0, At, B0); PG8_MMA(0, 1, At, B1); PG8_BAR; PG8_SCHED;
;             PG8_LDA(At, 0, 1); PG8_STAGE(PG8_SB(0, 0), b2, voffB); PG8_STAGE(PG8_SB(0, 1), b2 + hstep, voffB); PG8_STAGE(PG8_SA(0, 0), a2, voffA);
.LBB0_770:
	s_add_u32 s65, s66, 0xfffc0080
	s_addc_u32 s68, s67, -1
	s_add_i32 s72, 0, 0x10000
	s_cmp_eq_u32 s63, 12
	s_cselect_b32 s71, s27, s68
	s_cselect_b32 s70, s53, s65
	v_add_u32_e32 v146, s72, v148
	s_cselect_b32 s69, s25, s56
	s_cselect_b32 s68, s54, s55
	s_add_i32 s65, 0, 0x14000
	ds_read_b128 v[142:145], v146
	ds_read_b128 v[152:155], v146 offset:1024
	ds_read_b128 v[156:159], v146 offset:2048
	ds_read_b128 v[160:163], v146 offset:3072
	v_add_u32_e32 v146, s65, v148
	ds_read_b128 v[164:167], v146
	ds_read_b128 v[168:171], v146 offset:1024
	ds_read_b128 v[172:175], v146 offset:2048
	ds_read_b128 v[180:183], v146 offset:3072
	v_lshl_add_u64 v[146:147], s[66:67], 0, v[140:141]
	s_add_i32 m0, s29, 0xc000
	ds_read_b128 v[184:187], v150
	ds_read_b128 v[200:203], v150 offset:1024
	ds_read_b128 v[204:207], v150 offset:2048
	ds_read_b128 v[208:211], v150 offset:3072
	ds_read_b128 v[212:215], v150 offset:4096
	ds_read_b128 v[216:219], v150 offset:5120
	ds_read_b128 v[220:223], v150 offset:6144
	ds_read_b128 v[224:227], v150 offset:7168
	global_load_lds_dwordx4 v[146:147], off
	v_lshl_add_u64 v[146:147], s[66:67], 0, v[138:139]
	s_add_i32 m0, s29, 0xe000
	s_nop 0
	global_load_lds_dwordx4 v[146:147], off
	s_waitcnt vmcnt(8)
	s_waitcnt lgkmcnt(0)
	s_barrier
	s_setprio 1
	v_mfma_f32_16x16x32_bf16 v[130:133], v[142:145], v[184:187], v[130:133]
	v_mfma_f32_16x16x32_bf16 v[126:129], v[156:159], v[184:187], v[126:129]
	v_mfma_f32_16x16x32_bf16 v[114:117], v[142:145], v[204:207], v[114:117]
	v_mfma_f32_16x16x32_bf16 v[110:113], v[156:159], v[204:207], v[110:113]
	v_mfma_f32_16x16x32_bf16 v[98:101], v[142:145], v[212:215], v[98:101]
	v_mfma_f32_16x16x32_bf16 v[94:97], v[156:159], v[212:215], v[94:97]
	v_mfma_f32_16x16x32_bf16 v[78:81], v[142:145], v[220:223], v[78:81]
	v_mfma_f32_16x16x32_bf16 v[74:77], v[156:159], v[220:223], v[74:77]
	v_mfma_f32_16x16x32_bf16 v[130:133], v[152:155], v[200:203], v[130:133]
	v_mfma_f32_16x16x32_bf16 v[126:129], v[160:163], v[200:203], v[126:129]
	v_mfma_f32_16x16x32_bf16 v[114:117], v[152:155], v[208:211], v[114:117]
	v_mfma_f32_16x16x32_bf16 v[110:113], v[160:163], v[208:211], v[110:113]
	v_mfma_f32_16x16x32_bf16 v[98:101], v[152:155], v[216:219], v[98:101]
	v_mfma_f32_16x16x32_bf16 v[94:97], v[160:163], v[216:219], v[94:97]
	v_mfma_f32_16x16x32_bf16 v[78:81], v[152:155], v[224:227], v[78:81]
	v_mfma_f32_16x16x32_bf16 v[74:77], v[160:163], v[224:227], v[74:77]
	v_mfma_f32_16x16x32_bf16 v[122:125], v[164:167], v[184:187], v[122:125]
	v_mfma_f32_16x16x32_bf16 v[118:121], v[172:175], v[184:187], v[118:121]
	v_mfma_f32_16x16x32_bf16 v[106:109], v[164:167], v[204:207], v[106:109]
	v_mfma_f32_16x16x32_bf16 v[102:105], v[172:175], v[204:207], v[102:105]
	v_mfma_f32_16x16x32_bf16 v[90:93], v[164:167], v[212:215], v[90:93]
	v_mfma_f32_16x16x32_bf16 v[86:89], v[172:175], v[212:215], v[86:89]
	v_mfma_f32_16x16x32_bf16 v[70:73], v[164:167], v[220:223], v[70:73]
	v_mfma_f32_16x16x32_bf16 v[66:69], v[172:175], v[220:223], v[66:69]
	v_mfma_f32_16x16x32_bf16 v[122:125], v[168:171], v[200:203], v[122:125]
	v_mfma_f32_16x16x32_bf16 v[118:121], v[180:183], v[200:203], v[118:121]
	v_mfma_f32_16x16x32_bf16 v[106:109], v[168:171], v[208:211], v[106:109]
	v_mfma_f32_16x16x32_bf16 v[102:105], v[180:183], v[208:211], v[102:105]
	v_mfma_f32_16x16x32_bf16 v[90:93], v[168:171], v[216:219], v[90:93]
	v_mfma_f32_16x16x32_bf16 v[86:89], v[180:183], v[216:219], v[86:89]
	v_mfma_f32_16x16x32_bf16 v[70:73], v[168:171], v[224:227], v[70:73]
	v_mfma_f32_16x16x32_bf16 v[66:69], v[180:183], v[224:227], v[66:69]
	s_setprio 0
	s_barrier
	s_add_i32 s72, s72, s28
	v_lshl_add_u64 v[146:147], s[68:69], 0, v[134:135]
	s_mov_b32 m0, s72
	ds_read_b128 v[184:187], v150 offset:16384
	ds_read_b128 v[200:203], v150 offset:17408
	ds_read_b128 v[204:207], v150 offset:18432
	ds_read_b128 v[208:211], v150 offset:19456
	ds_read_b128 v[212:215], v150 offset:20480
	ds_read_b128 v[216:219], v150 offset:21504
	ds_read_b128 v[220:223], v150 offset:22528
	ds_read_b128 v[224:227], v150 offset:23552
	global_load_lds_dwordx4 v[146:147], off
	s_add_i32 m0, s72, 0x2000
	s_add_u32 s72, s68, 0x40000
	v_lshl_add_u64 v[176:177], s[68:69], 0, v[136:137]
	s_addc_u32 s73, s69, 0
	s_add_i32 s65, s65, s28
	global_load_lds_dwordx4 v[176:177], off
	v_lshl_add_u64 v[228:229], s[72:73], 0, v[134:135]
	s_mov_b32 m0, s65
	v_lshl_add_u64 v[230:231], s[70:71], 0, v[136:137]
	global_load_lds_dwordx4 v[228:229], off
	v_lshl_add_u64 v[228:229], s[72:73], 0, v[136:137]
	s_add_i32 m0, s65, 0x2000
	s_nop 0
	global_load_lds_dwordx4 v[228:229], off
	v_lshl_add_u64 v[228:229], s[70:71], 0, v[134:135]
	s_mov_b32 m0, s29
	s_nop 0
	global_load_lds_dwordx4 v[228:229], off
	s_mov_b32 m0, s34
	s_nop 0
	global_load_lds_dwordx4 v[230:231], off
	s_waitcnt vmcnt(8)
	s_waitcnt lgkmcnt(0)
	s_barrier
; #define PG8_STAGE(bufoff, gbase, voff) do { _Pragma("unroll") for (int _i = 0; _i < 2; ++_i) \
;         __builtin_amdgcn_global_load_lds((const unsigned*)((const char*)(gbase) + (voff)[_i]), (PG8_LAS unsigned*)(lds + (bufoff) + ldsw + _i * 8192), 16, 0, 0); } while (0)
; #define PG8_LDA(dst, b, h) do { _Pragma("unroll") for (int m = 0; m < 4; ++m) _Pragma("unroll") for (int k = 0; k < 2; ++k) dst[m][k] = *(const PG8_LAS bf16x8*)(lds + PG8_SA(b, h) + aoff + m * 2048 + k * 1024); } while (0)
; #define PG8_LDB(dst, b, h) do { _Pragma("unroll") for (int n = 0; n < 2; ++n) _Pragma("unroll") for (int k = 0; k < 2; ++k) dst[n][k] = *(const PG8_LAS bf16x8*)(lds + PG8_SB(b, h) + boff + n * 2048 + k * 1024); } while (0)
; #define PG8_MMA(ai, bj, At, Bt) do { __builtin_amdgcn_s_setprio(1); _Pragma("unroll") for (int m = 0; m < 4; ++m) _Pragma("unroll") for (int n = 0; n < 2; ++n) _Pragma("unroll") for (int k = 0; k < 2; ++k) \
;         acc[ai][bj][m][n] = __builtin_amdgcn_mfma_f32_16x16x32_bf16(Bt[n][k], At[m][k], acc[ai][bj][m][n], 0, 0, 0); __builtin_amdgcn_s_setprio(0); } while (0)
; #define PG8_WAIT_V(n) asm volatile("s_waitcnt vmcnt(" #n ")" ::: "memory")
; #define PG8_WAIT_L(n) asm volatile("s_waitcnt lgkmcnt(" #n ")" ::: "memory")
; #define PG8_BAR __builtin_amdgcn_s_barrier()
; #define PG8_SCHED __builtin_amdgcn_sched_barrier(0)
; template <class Epi, class Sched, bool ALIGN_EPI = false, bool SP2 = false>
; __device__ __forceinline__ void gemm_phase(PG8_LAS unsigned char* lds, const Gemm g, const Sched& S, const Epi& E) {
;     ...
;             PG8_WAIT_V(8); PG8_WAIT_L(0); PG8_BAR; PG8_MMA(1, 0, At, B0); PG8_MMA(1, 1, At, B1); PG8_BAR; PG8_SCHED;
;             PG8_LDB(B0, 1, 0); PG8_LDB(B1, 1, 1); PG8_SCHED; PG8_LDA(At, 1, 0); PG8_STAGE(PG8_SA(0, 1), a2 + hstep, voffA);
;             PG8_WAIT_V(8); PG8_WAIT_L(0); PG8_BAR; PG8_MMA(0, 0, At, B0); PG8_MMA(0, 1, At, B1); PG8_BAR; PG8_SCHED;
	s_setprio 1
	v_mfma_f32_16x16x32_bf16 v[62:65], v[142:145], v[184:187], v[62:65]
	v_mfma_f32_16x16x32_bf16 v[58:61], v[156:159], v[184:187], v[58:61]
	v_mfma_f32_16x16x32_bf16 v[46:49], v[142:145], v[204:207], v[46:49]
	v_mfma_f32_16x16x32_bf16 v[42:45], v[156:159], v[204:207], v[42:45]
	v_mfma_f32_16x16x32_bf16 v[30:33], v[142:145], v[212:215], v[30:33]
	v_mfma_f32_16x16x32_bf16 v[26:29], v[156:159], v[212:215], v[26:29]
	v_mfma_f32_16x16x32_bf16 v[14:17], v[142:145], v[220:223], v[14:17]
	v_mfma_f32_16x16x32_bf16 v[10:13], v[156:159], v[220:223], v[10:13]
	v_mfma_f32_16x16x32_bf16 v[62:65], v[152:155], v[200:203], v[62:65]
	v_mfma_f32_16x16x32_bf16 v[58:61], v[160:163], v[200:203], v[58:61]
	v_mfma_f32_16x16x32_bf16 v[46:49], v[152:155], v[208:211], v[46:49]
	v_mfma_f32_16x16x32_bf16 v[42:45], v[160:163], v[208:211], v[42:45]
	v_mfma_f32_16x16x32_bf16 v[30:33], v[152:155], v[216:219], v[30:33]
	v_mfma_f32_16x16x32_bf16 v[26:29], v[160:163], v[216:219], v[26:29]
	v_mfma_f32_16x16x32_bf16 v[14:17], v[152:155], v[224:227], v[14:17]
	v_mfma_f32_16x16x32_bf16 v[10:13], v[160:163], v[224:227], v[10:13]
	v_mfma_f32_16x16x32_bf16 v[54:57], v[164:167], v[184:187], v[54:57]
	v_mfma_f32_16x16x32_bf16 v[50:53], v[172:175], v[184:187], v[50:53]
	v_mfma_f32_16x16x32_bf16 v[38:41], v[164:167], v[204:207], v[38:41]
	v_mfma_f32_16x16x32_bf16 v[34:37], v[172:175], v[204:207], v[34:37]
	v_mfma_f32_16x16x32_bf16 v[22:25], v[164:167], v[212:215], v[22:25]
	v_mfma_f32_16x16x32_bf16 v[18:21], v[172:175], v[212:215], v[18:21]
	v_mfma_f32_16x16x32_bf16 v[6:9], v[164:167], v[220:223], v[6:9]
	v_mfma_f32_16x16x32_bf16 v[2:5], v[172:175], v[220:223], v[2:5]
	v_mfma_f32_16x16x32_bf16 v[54:57], v[168:171], v[200:203], v[54:57]
	v_mfma_f32_16x16x32_bf16 v[50:53], v[180:183], v[200:203], v[50:53]
	v_mfma_f32_16x16x32_bf16 v[38:41], v[168:171], v[208:211], v[38:41]
	v_mfma_f32_16x16x32_bf16 v[34:37], v[180:183], v[208:211], v[34:37]
	v_mfma_f32_16x16x32_bf16 v[22:25], v[168:171], v[216:219], v[22:25]
	v_mfma_f32_16x16x32_bf16 v[18:21], v[180:183], v[216:219], v[18:21]
	v_mfma_f32_16x16x32_bf16 v[6:9], v[168:171], v[224:227], v[6:9]
	v_mfma_f32_16x16x32_bf16 v[2:5], v[180:183], v[224:227], v[2:5]
	s_setprio 0
	s_barrier
	s_add_i32 s65, 0, 0x18000
	v_add_u32_e32 v151, s65, v148
	s_add_i32 s72, 0, 0x1c000
	ds_read_b128 v[142:145], v151
	ds_read_b128 v[152:155], v151 offset:1024
	ds_read_b128 v[156:159], v151 offset:2048
	ds_read_b128 v[160:163], v151 offset:3072
	v_add_u32_e32 v151, s72, v148
	ds_read_b128 v[164:167], v151
	ds_read_b128 v[168:171], v151 offset:1024
	ds_read_b128 v[172:175], v151 offset:2048
	ds_read_b128 v[180:183], v151 offset:3072
	s_add_u32 s70, s70, 0x40000
	s_addc_u32 s71, s71, 0
	s_mov_b32 m0, s36
	v_lshl_add_u64 v[232:233], s[70:71], 0, v[134:135]
	ds_read_b128 v[184:187], v150 offset:32768
	ds_read_b128 v[200:203], v150 offset:33792
	ds_read_b128 v[204:207], v150 offset:34816
	ds_read_b128 v[208:211], v150 offset:35840
	ds_read_b128 v[212:215], v150 offset:36864
	ds_read_b128 v[216:219], v150 offset:37888
	ds_read_b128 v[220:223], v150 offset:38912
	ds_read_b128 v[224:227], v150 offset:39936
	global_load_lds_dwordx4 v[232:233], off
	v_lshl_add_u64 v[232:233], s[70:71], 0, v[136:137]
	s_mov_b32 m0, s37
	s_nop 0
	global_load_lds_dwordx4 v[232:233], off
	s_waitcnt vmcnt(8)
	s_waitcnt lgkmcnt(0)
	s_barrier
	s_setprio 1
	v_mfma_f32_16x16x32_bf16 v[130:133], v[142:145], v[184:187], v[130:133]
	v_mfma_f32_16x16x32_bf16 v[126:129], v[156:159], v[184:187], v[126:129]
	v_mfma_f32_16x16x32_bf16 v[114:117], v[142:145], v[204:207], v[114:117]
	v_mfma_f32_16x16x32_bf16 v[110:113], v[156:159], v[204:207], v[110:113]
	v_mfma_f32_16x16x32_bf16 v[98:101], v[142:145], v[212:215], v[98:101]
	v_mfma_f32_16x16x32_bf16 v[94:97], v[156:159], v[212:215], v[94:97]
	v_mfma_f32_16x16x32_bf16 v[78:81], v[142:145], v[220:223], v[78:81]
	v_mfma_f32_16x16x32_bf16 v[74:77], v[156:159], v[220:223], v[74:77]
	v_mfma_f32_16x16x32_bf16 v[130:133], v[152:155], v[200:203], v[130:133]
	v_mfma_f32_16x16x32_bf16 v[126:129], v[160:163], v[200:203], v[126:129]
	v_mfma_f32_16x16x32_bf16 v[114:117], v[152:155], v[208:211], v[114:117]
	v_mfma_f32_16x16x32_bf16 v[110:113], v[160:163], v[208:211], v[110:113]
	v_mfma_f32_16x16x32_bf16 v[98:101], v[152:155], v[216:219], v[98:101]
	v_mfma_f32_16x16x32_bf16 v[94:97], v[160:163], v[216:219], v[94:97]
	v_mfma_f32_16x16x32_bf16 v[78:81], v[152:155], v[224:227], v[78:81]
	v_mfma_f32_16x16x32_bf16 v[74:77], v[160:163], v[224:227], v[74:77]
	v_mfma_f32_16x16x32_bf16 v[122:125], v[164:167], v[184:187], v[122:125]
	v_mfma_f32_16x16x32_bf16 v[118:121], v[172:175], v[184:187], v[118:121]
	v_mfma_f32_16x16x32_bf16 v[106:109], v[164:167], v[204:207], v[106:109]
	v_mfma_f32_16x16x32_bf16 v[102:105], v[172:175], v[204:207], v[102:105]
	v_mfma_f32_16x16x32_bf16 v[90:93], v[164:167], v[212:215], v[90:93]
	v_mfma_f32_16x16x32_bf16 v[86:89], v[172:175], v[212:215], v[86:89]
	v_mfma_f32_16x16x32_bf16 v[70:73], v[164:167], v[220:223], v[70:73]
	v_mfma_f32_16x16x32_bf16 v[66:69], v[172:175], v[220:223], v[66:69]
	v_mfma_f32_16x16x32_bf16 v[122:125], v[168:171], v[200:203], v[122:125]
	v_mfma_f32_16x16x32_bf16 v[118:121], v[180:183], v[200:203], v[118:121]
	v_mfma_f32_16x16x32_bf16 v[106:109], v[168:171], v[208:211], v[106:109]
	v_mfma_f32_16x16x32_bf16 v[102:105], v[180:183], v[208:211], v[102:105]
	v_mfma_f32_16x16x32_bf16 v[90:93], v[168:171], v[216:219], v[90:93]
	v_mfma_f32_16x16x32_bf16 v[86:89], v[180:183], v[216:219], v[86:89]
	v_mfma_f32_16x16x32_bf16 v[70:73], v[168:171], v[224:227], v[70:73]
	v_mfma_f32_16x16x32_bf16 v[66:69], v[180:183], v[224:227], v[66:69]
	s_setprio 0
	s_barrier
; #define PG8_STAGE(bufoff, gbase, voff) do { _Pragma("unroll") for (int _i = 0; _i < 2; ++_i) \
;         __builtin_amdgcn_global_load_lds((const unsigned*)((const char*)(gbase) + (voff)[_i]), (PG8_LAS unsigned*)(lds + (bufoff) + ldsw + _i * 8192), 16, 0, 0); } while (0)
; #define PG8_LDA(dst, b, h) do { _Pragma("unroll") for (int m = 0; m < 4; ++m) _Pragma("unroll") for (int k = 0; k < 2; ++k) dst[m][k] = *(const PG8_LAS bf16x8*)(lds + PG8_SA(b, h) + aoff + m * 2048 + k * 1024); } while (0)
; #define PG8_MMA(ai, bj, At, Bt) do { __builtin_amdgcn_s_setprio(1); _Pragma("unroll") for (int m = 0; m < 4; ++m) _Pragma("unroll") for (int n = 0; n < 2; ++n) _Pragma("unroll") for (int k = 0; k < 2; ++k) \
;         acc[ai][bj][m][n] = __builtin_amdgcn_mfma_f32_16x16x32_bf16(Bt[n][k], At[m][k], acc[ai][bj][m][n], 0, 0, 0); __builtin_amdgcn_s_setprio(0); } while (0)
; #define PG8_WAIT_V(n) asm volatile("s_waitcnt vmcnt(" #n ")" ::: "memory")
; #define PG8_WAIT_L(n) asm volatile("s_waitcnt lgkmcnt(" #n ")" ::: "memory")
; #define PG8_BAR __builtin_amdgcn_s_barrier()
; #define PG8_SCHED __builtin_amdgcn_sched_barrier(0)
; template <class Epi, class Sched, bool ALIGN_EPI = false, bool SP2 = false>
; __device__ __forceinline__ void gemm_phase(PG8_LAS unsigned char* lds, const Gemm g, const Sched& S, const Epi& E) {
;     ...
;         for (int t = 0; t < nt; t += 2) {
;             const bool last = (t == nt - 2);
;             const char* a1 = cA + (size_t)(t + 1) * kstep;
;             const char* a2 = last ? nA : cA + (size_t)(t + 2) * kstep; const char* b2 = last ? nB : cB + (size_t)(t + 2) * kstep;
;     ...
;             PG8_LDA(At, 1, 1); PG8_STAGE(PG8_SB(1, 0), b3, voffB); PG8_STAGE(PG8_SB(1, 1), b3 + hstep, voffB); PG8_STAGE(PG8_SA(1, 0), a3, voffA);
;             PG8_WAIT_V(8); PG8_WAIT_L(0); PG8_BAR; PG8_MMA(1, 0, At, B0); PG8_MMA(1, 1, At, B1); PG8_BAR; PG8_SCHED;
	s_add_i32 s65, s65, s28
	v_lshl_add_u64 v[146:147], v[146:147], 0, s[38:39]
	s_mov_b32 m0, s65
	ds_read_b128 v[184:187], v150 offset:49152
	ds_read_b128 v[200:203], v150 offset:50176
	ds_read_b128 v[204:207], v150 offset:51200
	ds_read_b128 v[208:211], v150 offset:52224
	ds_read_b128 v[212:215], v150 offset:53248
	ds_read_b128 v[216:219], v150 offset:54272
	ds_read_b128 v[220:223], v150 offset:55296
	ds_read_b128 v[224:227], v150 offset:56320
	global_load_lds_dwordx4 v[146:147], off
	s_add_i32 m0, s65, 0x2000
	s_add_u32 s68, s68, 0x40080
	v_lshl_add_u64 v[146:147], v[176:177], 0, s[38:39]
	s_addc_u32 s69, s69, 0
	s_add_i32 s65, s72, s28
	global_load_lds_dwordx4 v[146:147], off
	v_lshl_add_u64 v[146:147], s[68:69], 0, v[134:135]
	s_mov_b32 m0, s65
	s_nop 0
	global_load_lds_dwordx4 v[146:147], off
	v_lshl_add_u64 v[146:147], s[68:69], 0, v[136:137]
	s_add_i32 m0, s65, 0x2000
	s_nop 0
	global_load_lds_dwordx4 v[146:147], off
	v_lshl_add_u64 v[146:147], v[228:229], 0, s[38:39]
	s_mov_b32 m0, s41
	s_nop 0
	global_load_lds_dwordx4 v[146:147], off
	v_lshl_add_u64 v[146:147], v[230:231], 0, s[38:39]
	s_mov_b32 m0, s42
	s_nop 0
	global_load_lds_dwordx4 v[146:147], off
	s_waitcnt vmcnt(8)
	s_waitcnt lgkmcnt(0)
	s_barrier
	s_setprio 1
	v_mfma_f32_16x16x32_bf16 v[62:65], v[142:145], v[184:187], v[62:65]
	v_mfma_f32_16x16x32_bf16 v[58:61], v[156:159], v[184:187], v[58:61]
	v_mfma_f32_16x16x32_bf16 v[46:49], v[142:145], v[204:207], v[46:49]
	v_mfma_f32_16x16x32_bf16 v[42:45], v[156:159], v[204:207], v[42:45]
	v_mfma_f32_16x16x32_bf16 v[30:33], v[142:145], v[212:215], v[30:33]
	v_mfma_f32_16x16x32_bf16 v[26:29], v[156:159], v[212:215], v[26:29]
	v_mfma_f32_16x16x32_bf16 v[14:17], v[142:145], v[220:223], v[14:17]
	v_mfma_f32_16x16x32_bf16 v[10:13], v[156:159], v[220:223], v[10:13]
	v_mfma_f32_16x16x32_bf16 v[62:65], v[152:155], v[200:203], v[62:65]
	v_mfma_f32_16x16x32_bf16 v[58:61], v[160:163], v[200:203], v[58:61]
	v_mfma_f32_16x16x32_bf16 v[46:49], v[152:155], v[208:211], v[46:49]
	v_mfma_f32_16x16x32_bf16 v[42:45], v[160:163], v[208:211], v[42:45]
	v_mfma_f32_16x16x32_bf16 v[30:33], v[152:155], v[216:219], v[30:33]
	v_mfma_f32_16x16x32_bf16 v[26:29], v[160:163], v[216:219], v[26:29]
	v_mfma_f32_16x16x32_bf16 v[14:17], v[152:155], v[224:227], v[14:17]
	v_mfma_f32_16x16x32_bf16 v[10:13], v[160:163], v[224:227], v[10:13]
	v_mfma_f32_16x16x32_bf16 v[54:57], v[164:167], v[184:187], v[54:57]
	v_mfma_f32_16x16x32_bf16 v[50:53], v[172:175], v[184:187], v[50:53]
	v_mfma_f32_16x16x32_bf16 v[38:41], v[164:167], v[204:207], v[38:41]
	v_mfma_f32_16x16x32_bf16 v[34:37], v[172:175], v[204:207], v[34:37]
	v_mfma_f32_16x16x32_bf16 v[22:25], v[164:167], v[212:215], v[22:25]
	v_mfma_f32_16x16x32_bf16 v[18:21], v[172:175], v[212:215], v[18:21]
	v_mfma_f32_16x16x32_bf16 v[6:9], v[164:167], v[220:223], v[6:9]
	v_mfma_f32_16x16x32_bf16 v[2:5], v[172:175], v[220:223], v[2:5]
	v_mfma_f32_16x16x32_bf16 v[54:57], v[168:171], v[200:203], v[54:57]
	v_mfma_f32_16x16x32_bf16 v[50:53], v[180:183], v[200:203], v[50:53]
	v_mfma_f32_16x16x32_bf16 v[38:41], v[168:171], v[208:211], v[38:41]
	v_mfma_f32_16x16x32_bf16 v[34:37], v[180:183], v[208:211], v[34:37]
	v_mfma_f32_16x16x32_bf16 v[22:25], v[168:171], v[216:219], v[22:25]
	v_mfma_f32_16x16x32_bf16 v[18:21], v[180:183], v[216:219], v[18:21]
	v_mfma_f32_16x16x32_bf16 v[6:9], v[168:171], v[224:227], v[6:9]
	v_mfma_f32_16x16x32_bf16 v[2:5], v[180:183], v[224:227], v[2:5]
	s_setprio 0
	s_barrier
	s_add_i32 s63, s63, 2
	s_add_u32 s55, s55, 0x100
	s_addc_u32 s56, s56, 0
	s_add_u32 s66, s66, 0x100
	s_addc_u32 s67, s67, 0
	s_cmp_gt_u32 s63, 13
	s_cbranch_scc0 .LBB0_770
	s_and_b64 vcc, exec, s[20:21]
	s_cbranch_vccz .LBB0_773
	s_barrier

; #define PG8_STAGE(bufoff, gbase, voff) do { _Pragma("unroll") for (int _i = 0; _i < 2; ++_i) \
;         __builtin_amdgcn_global_load_lds((const unsigned*)((const char*)(gbase) + (voff)[_i]), (PG8_LAS unsigned*)(lds + (bufoff) + ldsw + _i * 8192), 16, 0, 0); } while (0)
; #define PG8_LDA(dst, b, h) do { _Pragma("unroll") for (int m = 0; m < 4; ++m) _Pragma("unroll") for (int k = 0; k < 2; ++k) dst[m][k] = *(const PG8_LAS bf16x8*)(lds + PG8_SA(b, h) + aoff + m * 2048 + k * 1024); } while (0)
; #define PG8_LDB(dst, b, h) do { _Pragma("unroll") for (int n = 0; n < 2; ++n) _Pragma("unroll") for (int k = 0; k < 2; ++k) dst[n][k] = *(const PG8_LAS bf16x8*)(lds + PG8_SB(b, h) + boff + n * 2048 + k * 1024); } while (0)
; #define PG8_MMA(ai, bj, At, Bt) do { __builtin_amdgcn_s_setprio(1); _Pragma("unroll") for (int m = 0; m < 4; ++m) _Pragma("unroll") for (int n = 0; n < 2; ++n) _Pragma("unroll") for (int k = 0; k < 2; ++k) \
;         acc[ai][bj][m][n] = __builtin_amdgcn_mfma_f32_16x16x32_bf16(Bt[n][k], At[m][k], acc[ai][bj][m][n], 0, 0, 0); __builtin_amdgcn_s_setprio(0); } while (0)
; #define PG8_WAIT_V(n) asm volatile("s_waitcnt vmcnt(" #n ")" ::: "memory")
; #define PG8_WAIT_L(n) asm volatile("s_waitcnt lgkmcnt(" #n ")" ::: "memory")
; #define PG8_BAR __builtin_amdgcn_s_barrier()
; #define PG8_SCHED __builtin_amdgcn_sched_barrier(0)
; template <class Epi, class Sched, bool ALIGN_EPI = false, bool SP2 = false>
; __device__ __forceinline__ void gemm_phase(PG8_LAS unsigned char* lds, const Gemm g, const Sched& S, const Epi& E) {
;     ...
;             const bool last = (t == nt - 2);
;             const char* a1 = cA + (size_t)(t + 1) * kstep;
;             const char* a2 = last ? nA : cA + (size_t)(t + 2) * kstep; const char* b2 = last ? nB : cB + (size_t)(t + 2) * kstep;
;             const char* a3 = a2 + kstep; const char* b3 = b2 + kstep;
;             if (last && has_next) S.a_ready(nxt);
;             if constexpr (SP2) {
;             PG8_LDB(B0, 0, 0); PG8_LDB(B1, 0, 1); PG8_SCHED; PG8_LDA(At, 0, 0); PG8_STAGE(PG8_SA(1, 1), a1 + hstep, voffA);
;             PG8_WAIT_V(8); PG8_WAIT_L(0); PG8_BAR; PG8_MMA(0, 0, At, B0); PG8_MMA(0, 1, At, B1); PG8_BAR; PG8_SCHED;
;             PG8_LDA(At, 0, 1); PG8_STAGE(PG8_SB(0, 0), b2, voffB); PG8_STAGE(PG8_SB(0, 1), b2 + hstep, voffB); PG8_STAGE(PG8_SA(0, 0), a2, voffA);
.LBB0_856:
	s_add_u32 s78, s76, 0xfffc0080
	s_addc_u32 s79, s77, -1
	s_add_i32 s84, 0, 0x10000
	s_cmp_eq_u32 s83, 12
	s_cselect_b32 s81, s56, s79
	s_cselect_b32 s80, s67, s78
	s_cselect_b32 s79, s65, s82
	s_cselect_b32 s78, s73, s75
	s_add_i32 s86, 0, 0x14000
	v_add_u32_e32 v146, s84, v177
	v_add_u32_e32 v174, s86, v177
	ds_read_b128 v[134:137], v146
	ds_read_b128 v[138:141], v146 offset:1024
	ds_read_b128 v[142:145], v146 offset:2048
	ds_read_b128 v[146:149], v146 offset:3072
	ds_read_b128 v[162:165], v174
	ds_read_b128 v[166:169], v174 offset:1024
	ds_read_b128 v[170:173], v174 offset:2048
	ds_read_b128 v[182:185], v174 offset:3072
	v_lshl_add_u64 v[174:175], s[76:77], 0, v[160:161]
	s_add_i32 m0, s36, 0xc000
	ds_read_b128 v[200:203], v180
	ds_read_b128 v[204:207], v180 offset:1024
	ds_read_b128 v[208:211], v180 offset:2048
	ds_read_b128 v[212:215], v180 offset:3072
	ds_read_b128 v[216:219], v180 offset:4096
	ds_read_b128 v[220:223], v180 offset:5120
	ds_read_b128 v[224:227], v180 offset:6144
	ds_read_b128 v[228:231], v180 offset:7168
	global_load_lds_dwordx4 v[174:175], off
	v_lshl_add_u64 v[174:175], s[76:77], 0, v[158:159]
	s_add_i32 m0, s36, 0xe000
	s_nop 0
	global_load_lds_dwordx4 v[174:175], off
	s_waitcnt vmcnt(8)
	s_waitcnt lgkmcnt(0)
	s_barrier
	s_setprio 1
	v_mfma_f32_16x16x32_bf16 v[130:133], v[134:137], v[200:203], v[130:133]
	v_mfma_f32_16x16x32_bf16 v[102:105], v[142:145], v[200:203], v[102:105]
	v_mfma_f32_16x16x32_bf16 v[126:129], v[134:137], v[208:211], v[126:129]
	v_mfma_f32_16x16x32_bf16 v[98:101], v[142:145], v[208:211], v[98:101]
	v_mfma_f32_16x16x32_bf16 v[122:125], v[134:137], v[216:219], v[122:125]
	v_mfma_f32_16x16x32_bf16 v[90:93], v[142:145], v[216:219], v[90:93]
	v_mfma_f32_16x16x32_bf16 v[118:121], v[134:137], v[224:227], v[118:121]
	v_mfma_f32_16x16x32_bf16 v[86:89], v[142:145], v[224:227], v[86:89]
	v_mfma_f32_16x16x32_bf16 v[130:133], v[138:141], v[204:207], v[130:133]
	v_mfma_f32_16x16x32_bf16 v[102:105], v[146:149], v[204:207], v[102:105]
	v_mfma_f32_16x16x32_bf16 v[126:129], v[138:141], v[212:215], v[126:129]
	v_mfma_f32_16x16x32_bf16 v[98:101], v[146:149], v[212:215], v[98:101]
	v_mfma_f32_16x16x32_bf16 v[122:125], v[138:141], v[220:223], v[122:125]
	v_mfma_f32_16x16x32_bf16 v[90:93], v[146:149], v[220:223], v[90:93]
	v_mfma_f32_16x16x32_bf16 v[118:121], v[138:141], v[228:231], v[118:121]
	v_mfma_f32_16x16x32_bf16 v[86:89], v[146:149], v[228:231], v[86:89]
	v_mfma_f32_16x16x32_bf16 v[94:97], v[162:165], v[200:203], v[94:97]
	v_mfma_f32_16x16x32_bf16 v[66:69], v[170:173], v[200:203], v[66:69]
	v_mfma_f32_16x16x32_bf16 v[114:117], v[162:165], v[208:211], v[114:117]
	v_mfma_f32_16x16x32_bf16 v[78:81], v[170:173], v[208:211], v[78:81]
	v_mfma_f32_16x16x32_bf16 v[110:113], v[162:165], v[216:219], v[110:113]
	v_mfma_f32_16x16x32_bf16 v[74:77], v[170:173], v[216:219], v[74:77]
	v_mfma_f32_16x16x32_bf16 v[106:109], v[162:165], v[224:227], v[106:109]
	v_mfma_f32_16x16x32_bf16 v[70:73], v[170:173], v[224:227], v[70:73]
	v_mfma_f32_16x16x32_bf16 v[94:97], v[166:169], v[204:207], v[94:97]
	v_mfma_f32_16x16x32_bf16 v[66:69], v[182:185], v[204:207], v[66:69]
	v_mfma_f32_16x16x32_bf16 v[114:117], v[166:169], v[212:215], v[114:117]
	v_mfma_f32_16x16x32_bf16 v[78:81], v[182:185], v[212:215], v[78:81]
	v_mfma_f32_16x16x32_bf16 v[110:113], v[166:169], v[220:223], v[110:113]
	v_mfma_f32_16x16x32_bf16 v[74:77], v[182:185], v[220:223], v[74:77]
	v_mfma_f32_16x16x32_bf16 v[106:109], v[166:169], v[228:231], v[106:109]
	v_mfma_f32_16x16x32_bf16 v[70:73], v[182:185], v[228:231], v[70:73]
	s_setprio 0
	s_barrier
	s_add_i32 s84, s84, s34
	v_lshl_add_u64 v[174:175], s[78:79], 0, v[152:153]
	s_mov_b32 m0, s84
	ds_read_b128 v[200:203], v180 offset:16384
	ds_read_b128 v[204:207], v180 offset:17408
	ds_read_b128 v[208:211], v180 offset:18432
	ds_read_b128 v[212:215], v180 offset:19456
	ds_read_b128 v[216:219], v180 offset:20480
	ds_read_b128 v[220:223], v180 offset:21504
	ds_read_b128 v[224:227], v180 offset:22528
	ds_read_b128 v[228:231], v180 offset:23552
	global_load_lds_dwordx4 v[174:175], off
	s_add_i32 m0, s84, 0x2000
	s_add_u32 s84, s78, 0x40000
	v_lshl_add_u64 v[186:187], s[78:79], 0, v[156:157]
	s_addc_u32 s85, s79, 0
	s_add_i32 s86, s86, s34
	global_load_lds_dwordx4 v[186:187], off
	v_lshl_add_u64 v[232:233], s[84:85], 0, v[152:153]
	s_mov_b32 m0, s86
	v_lshl_add_u64 v[234:235], s[80:81], 0, v[154:155]
	global_load_lds_dwordx4 v[232:233], off
	v_lshl_add_u64 v[232:233], s[84:85], 0, v[156:157]
	s_add_i32 m0, s86, 0x2000
	s_nop 0
	global_load_lds_dwordx4 v[232:233], off
	v_lshl_add_u64 v[232:233], s[80:81], 0, v[150:151]
	s_mov_b32 m0, s36
	s_nop 0
	global_load_lds_dwordx4 v[232:233], off
	s_mov_b32 m0, s37
	s_nop 0
	global_load_lds_dwordx4 v[234:235], off
	s_waitcnt vmcnt(8)
	s_waitcnt lgkmcnt(0)
	s_barrier
; #define PG8_STAGE(bufoff, gbase, voff) do { _Pragma("unroll") for (int _i = 0; _i < 2; ++_i) \
;         __builtin_amdgcn_global_load_lds((const unsigned*)((const char*)(gbase) + (voff)[_i]), (PG8_LAS unsigned*)(lds + (bufoff) + ldsw + _i * 8192), 16, 0, 0); } while (0)
; #define PG8_LDA(dst, b, h) do { _Pragma("unroll") for (int m = 0; m < 4; ++m) _Pragma("unroll") for (int k = 0; k < 2; ++k) dst[m][k] = *(const PG8_LAS bf16x8*)(lds + PG8_SA(b, h) + aoff + m * 2048 + k * 1024); } while (0)
; #define PG8_LDB(dst, b, h) do { _Pragma("unroll") for (int n = 0; n < 2; ++n) _Pragma("unroll") for (int k = 0; k < 2; ++k) dst[n][k] = *(const PG8_LAS bf16x8*)(lds + PG8_SB(b, h) + boff + n * 2048 + k * 1024); } while (0)
; #define PG8_MMA(ai, bj, At, Bt) do { __builtin_amdgcn_s_setprio(1); _Pragma("unroll") for (int m = 0; m < 4; ++m) _Pragma("unroll") for (int n = 0; n < 2; ++n) _Pragma("unroll") for (int k = 0; k < 2; ++k) \
;         acc[ai][bj][m][n] = __builtin_amdgcn_mfma_f32_16x16x32_bf16(Bt[n][k], At[m][k], acc[ai][bj][m][n], 0, 0, 0); __builtin_amdgcn_s_setprio(0); } while (0)
; #define PG8_WAIT_V(n) asm volatile("s_waitcnt vmcnt(" #n ")" ::: "memory")
; #define PG8_WAIT_L(n) asm volatile("s_waitcnt lgkmcnt(" #n ")" ::: "memory")
; #define PG8_BAR __builtin_amdgcn_s_barrier()
; #define PG8_SCHED __builtin_amdgcn_sched_barrier(0)
; template <class Epi, class Sched, bool ALIGN_EPI = false, bool SP2 = false>
; __device__ __forceinline__ void gemm_phase(PG8_LAS unsigned char* lds, const Gemm g, const Sched& S, const Epi& E) {
;     ...
;             PG8_WAIT_V(8); PG8_WAIT_L(0); PG8_BAR; PG8_MMA(1, 0, At, B0); PG8_MMA(1, 1, At, B1); PG8_BAR; PG8_SCHED;
;             PG8_LDB(B0, 1, 0); PG8_LDB(B1, 1, 1); PG8_SCHED; PG8_LDA(At, 1, 0); PG8_STAGE(PG8_SA(0, 1), a2 + hstep, voffA);
;             PG8_WAIT_V(8); PG8_WAIT_L(0); PG8_BAR; PG8_MMA(0, 0, At, B0); PG8_MMA(0, 1, At, B1); PG8_BAR; PG8_SCHED;
	s_setprio 1
	v_mfma_f32_16x16x32_bf16 v[62:65], v[134:137], v[200:203], v[62:65]
	v_mfma_f32_16x16x32_bf16 v[30:33], v[142:145], v[200:203], v[30:33]
	v_mfma_f32_16x16x32_bf16 v[58:61], v[134:137], v[208:211], v[58:61]
	v_mfma_f32_16x16x32_bf16 v[26:29], v[142:145], v[208:211], v[26:29]
	v_mfma_f32_16x16x32_bf16 v[54:57], v[134:137], v[216:219], v[54:57]
	v_mfma_f32_16x16x32_bf16 v[22:25], v[142:145], v[216:219], v[22:25]
	v_mfma_f32_16x16x32_bf16 v[50:53], v[134:137], v[224:227], v[50:53]
	v_mfma_f32_16x16x32_bf16 v[18:21], v[142:145], v[224:227], v[18:21]
	v_mfma_f32_16x16x32_bf16 v[62:65], v[138:141], v[204:207], v[62:65]
	v_mfma_f32_16x16x32_bf16 v[30:33], v[146:149], v[204:207], v[30:33]
	v_mfma_f32_16x16x32_bf16 v[58:61], v[138:141], v[212:215], v[58:61]
	v_mfma_f32_16x16x32_bf16 v[26:29], v[146:149], v[212:215], v[26:29]
	v_mfma_f32_16x16x32_bf16 v[54:57], v[138:141], v[220:223], v[54:57]
	v_mfma_f32_16x16x32_bf16 v[22:25], v[146:149], v[220:223], v[22:25]
	v_mfma_f32_16x16x32_bf16 v[50:53], v[138:141], v[228:231], v[50:53]
	v_mfma_f32_16x16x32_bf16 v[18:21], v[146:149], v[228:231], v[18:21]
	v_mfma_f32_16x16x32_bf16 v[34:37], v[162:165], v[200:203], v[34:37]
	v_mfma_f32_16x16x32_bf16 v[2:5], v[170:173], v[200:203], v[2:5]
	v_mfma_f32_16x16x32_bf16 v[46:49], v[162:165], v[208:211], v[46:49]
	v_mfma_f32_16x16x32_bf16 v[14:17], v[170:173], v[208:211], v[14:17]
	v_mfma_f32_16x16x32_bf16 v[42:45], v[162:165], v[216:219], v[42:45]
	v_mfma_f32_16x16x32_bf16 v[10:13], v[170:173], v[216:219], v[10:13]
	v_mfma_f32_16x16x32_bf16 v[38:41], v[162:165], v[224:227], v[38:41]
	v_mfma_f32_16x16x32_bf16 v[6:9], v[170:173], v[224:227], v[6:9]
	v_mfma_f32_16x16x32_bf16 v[34:37], v[166:169], v[204:207], v[34:37]
	v_mfma_f32_16x16x32_bf16 v[2:5], v[182:185], v[204:207], v[2:5]
	v_mfma_f32_16x16x32_bf16 v[46:49], v[166:169], v[212:215], v[46:49]
	v_mfma_f32_16x16x32_bf16 v[14:17], v[182:185], v[212:215], v[14:17]
	v_mfma_f32_16x16x32_bf16 v[42:45], v[166:169], v[220:223], v[42:45]
	v_mfma_f32_16x16x32_bf16 v[10:13], v[182:185], v[220:223], v[10:13]
	v_mfma_f32_16x16x32_bf16 v[38:41], v[166:169], v[228:231], v[38:41]
	v_mfma_f32_16x16x32_bf16 v[6:9], v[182:185], v[228:231], v[6:9]
	s_setprio 0
	s_barrier
	s_add_i32 s84, 0, 0x18000
	s_add_i32 s85, 0, 0x1c000
	v_add_u32_e32 v146, s84, v177
	v_add_u32_e32 v181, s85, v177
	ds_read_b128 v[134:137], v146
	ds_read_b128 v[138:141], v146 offset:1024
	ds_read_b128 v[142:145], v146 offset:2048
	ds_read_b128 v[146:149], v146 offset:3072
	ds_read_b128 v[162:165], v181
	ds_read_b128 v[166:169], v181 offset:1024
	ds_read_b128 v[170:173], v181 offset:2048
	ds_read_b128 v[182:185], v181 offset:3072
	s_add_u32 s80, s80, 0x40000
	s_addc_u32 s81, s81, 0
	s_mov_b32 m0, s40
	v_lshl_add_u64 v[236:237], s[80:81], 0, v[150:151]
	ds_read_b128 v[200:203], v180 offset:32768
	ds_read_b128 v[204:207], v180 offset:33792
	ds_read_b128 v[208:211], v180 offset:34816
	ds_read_b128 v[212:215], v180 offset:35840
	ds_read_b128 v[216:219], v180 offset:36864
	ds_read_b128 v[220:223], v180 offset:37888
	ds_read_b128 v[224:227], v180 offset:38912
	ds_read_b128 v[228:231], v180 offset:39936
	global_load_lds_dwordx4 v[236:237], off
	v_lshl_add_u64 v[236:237], s[80:81], 0, v[154:155]
	s_mov_b32 m0, s41
	s_nop 0
	global_load_lds_dwordx4 v[236:237], off
	s_waitcnt vmcnt(8)
	s_waitcnt lgkmcnt(0)
	s_barrier
	s_setprio 1
	v_mfma_f32_16x16x32_bf16 v[130:133], v[134:137], v[200:203], v[130:133]
	v_mfma_f32_16x16x32_bf16 v[102:105], v[142:145], v[200:203], v[102:105]
	v_mfma_f32_16x16x32_bf16 v[126:129], v[134:137], v[208:211], v[126:129]
	v_mfma_f32_16x16x32_bf16 v[98:101], v[142:145], v[208:211], v[98:101]
	v_mfma_f32_16x16x32_bf16 v[122:125], v[134:137], v[216:219], v[122:125]
	v_mfma_f32_16x16x32_bf16 v[90:93], v[142:145], v[216:219], v[90:93]
	v_mfma_f32_16x16x32_bf16 v[118:121], v[134:137], v[224:227], v[118:121]
	v_mfma_f32_16x16x32_bf16 v[86:89], v[142:145], v[224:227], v[86:89]
	v_mfma_f32_16x16x32_bf16 v[130:133], v[138:141], v[204:207], v[130:133]
	v_mfma_f32_16x16x32_bf16 v[102:105], v[146:149], v[204:207], v[102:105]
	v_mfma_f32_16x16x32_bf16 v[126:129], v[138:141], v[212:215], v[126:129]
	v_mfma_f32_16x16x32_bf16 v[98:101], v[146:149], v[212:215], v[98:101]
	v_mfma_f32_16x16x32_bf16 v[122:125], v[138:141], v[220:223], v[122:125]
	v_mfma_f32_16x16x32_bf16 v[90:93], v[146:149], v[220:223], v[90:93]
	v_mfma_f32_16x16x32_bf16 v[118:121], v[138:141], v[228:231], v[118:121]
	v_mfma_f32_16x16x32_bf16 v[86:89], v[146:149], v[228:231], v[86:89]
	v_mfma_f32_16x16x32_bf16 v[94:97], v[162:165], v[200:203], v[94:97]
	v_mfma_f32_16x16x32_bf16 v[66:69], v[170:173], v[200:203], v[66:69]
	v_mfma_f32_16x16x32_bf16 v[114:117], v[162:165], v[208:211], v[114:117]
	v_mfma_f32_16x16x32_bf16 v[78:81], v[170:173], v[208:211], v[78:81]
	v_mfma_f32_16x16x32_bf16 v[110:113], v[162:165], v[216:219], v[110:113]
	v_mfma_f32_16x16x32_bf16 v[74:77], v[170:173], v[216:219], v[74:77]
	v_mfma_f32_16x16x32_bf16 v[106:109], v[162:165], v[224:227], v[106:109]
	v_mfma_f32_16x16x32_bf16 v[70:73], v[170:173], v[224:227], v[70:73]
	v_mfma_f32_16x16x32_bf16 v[94:97], v[166:169], v[204:207], v[94:97]
	v_mfma_f32_16x16x32_bf16 v[66:69], v[182:185], v[204:207], v[66:69]
	v_mfma_f32_16x16x32_bf16 v[114:117], v[166:169], v[212:215], v[114:117]
	v_mfma_f32_16x16x32_bf16 v[78:81], v[182:185], v[212:215], v[78:81]
	v_mfma_f32_16x16x32_bf16 v[110:113], v[166:169], v[220:223], v[110:113]
	v_mfma_f32_16x16x32_bf16 v[74:77], v[182:185], v[220:223], v[74:77]
	v_mfma_f32_16x16x32_bf16 v[106:109], v[166:169], v[228:231], v[106:109]
	v_mfma_f32_16x16x32_bf16 v[70:73], v[182:185], v[228:231], v[70:73]
	s_setprio 0
	s_barrier
; #define PG8_STAGE(bufoff, gbase, voff) do { _Pragma("unroll") for (int _i = 0; _i < 2; ++_i) \
;         __builtin_amdgcn_global_load_lds((const unsigned*)((const char*)(gbase) + (voff)[_i]), (PG8_LAS unsigned*)(lds + (bufoff) + ldsw + _i * 8192), 16, 0, 0); } while (0)
; #define PG8_LDA(dst, b, h) do { _Pragma("unroll") for (int m = 0; m < 4; ++m) _Pragma("unroll") for (int k = 0; k < 2; ++k) dst[m][k] = *(const PG8_LAS bf16x8*)(lds + PG8_SA(b, h) + aoff + m * 2048 + k * 1024); } while (0)
; #define PG8_MMA(ai, bj, At, Bt) do { __builtin_amdgcn_s_setprio(1); _Pragma("unroll") for (int m = 0; m < 4; ++m) _Pragma("unroll") for (int n = 0; n < 2; ++n) _Pragma("unroll") for (int k = 0; k < 2; ++k) \
;         acc[ai][bj][m][n] = __builtin_amdgcn_mfma_f32_16x16x32_bf16(Bt[n][k], At[m][k], acc[ai][bj][m][n], 0, 0, 0); __builtin_amdgcn_s_setprio(0); } while (0)
; #define PG8_WAIT_V(n) asm volatile("s_waitcnt vmcnt(" #n ")" ::: "memory")
; #define PG8_WAIT_L(n) asm volatile("s_waitcnt lgkmcnt(" #n ")" ::: "memory")
; #define PG8_BAR __builtin_amdgcn_s_barrier()
; #define PG8_SCHED __builtin_amdgcn_sched_barrier(0)
; template <class Epi, class Sched, bool ALIGN_EPI = false, bool SP2 = false>
; __device__ __forceinline__ void gemm_phase(PG8_LAS unsigned char* lds, const Gemm g, const Sched& S, const Epi& E) {
;     ...
;         for (int t = 0; t < nt; t += 2) {
;             const bool last = (t == nt - 2);
;             const char* a1 = cA + (size_t)(t + 1) * kstep;
;             const char* a2 = last ? nA : cA + (size_t)(t + 2) * kstep; const char* b2 = last ? nB : cB + (size_t)(t + 2) * kstep;
;     ...
;             PG8_LDA(At, 1, 1); PG8_STAGE(PG8_SB(1, 0), b3, voffB); PG8_STAGE(PG8_SB(1, 1), b3 + hstep, voffB); PG8_STAGE(PG8_SA(1, 0), a3, voffA);
;             PG8_WAIT_V(8); PG8_WAIT_L(0); PG8_BAR; PG8_MMA(1, 0, At, B0); PG8_MMA(1, 1, At, B1); PG8_BAR; PG8_SCHED;
	s_add_i32 s80, s84, s34
	v_lshl_add_u64 v[174:175], v[174:175], 0, s[38:39]
	s_mov_b32 m0, s80
	ds_read_b128 v[200:203], v180 offset:49152
	ds_read_b128 v[204:207], v180 offset:50176
	ds_read_b128 v[208:211], v180 offset:51200
	ds_read_b128 v[212:215], v180 offset:52224
	ds_read_b128 v[216:219], v180 offset:53248
	ds_read_b128 v[220:223], v180 offset:54272
	ds_read_b128 v[224:227], v180 offset:55296
	ds_read_b128 v[228:231], v180 offset:56320
	global_load_lds_dwordx4 v[174:175], off
	s_add_i32 m0, s80, 0x2000
	s_add_u32 s78, s78, 0x40080
	v_lshl_add_u64 v[174:175], v[186:187], 0, s[38:39]
	s_addc_u32 s79, s79, 0
	s_add_i32 s80, s85, s34
	global_load_lds_dwordx4 v[174:175], off
	v_lshl_add_u64 v[174:175], s[78:79], 0, v[152:153]
	s_mov_b32 m0, s80
	s_nop 0
	global_load_lds_dwordx4 v[174:175], off
	v_lshl_add_u64 v[174:175], s[78:79], 0, v[156:157]
	s_add_i32 m0, s80, 0x2000
	s_nop 0
	global_load_lds_dwordx4 v[174:175], off
	v_lshl_add_u64 v[174:175], v[232:233], 0, s[38:39]
	s_mov_b32 m0, s52
	s_nop 0
	global_load_lds_dwordx4 v[174:175], off
	v_lshl_add_u64 v[174:175], v[234:235], 0, s[38:39]
	s_mov_b32 m0, s53
	s_nop 0
	global_load_lds_dwordx4 v[174:175], off
	s_waitcnt vmcnt(8)
	s_waitcnt lgkmcnt(0)
	s_barrier
	s_setprio 1
	v_mfma_f32_16x16x32_bf16 v[62:65], v[134:137], v[200:203], v[62:65]
	v_mfma_f32_16x16x32_bf16 v[30:33], v[142:145], v[200:203], v[30:33]
	v_mfma_f32_16x16x32_bf16 v[58:61], v[134:137], v[208:211], v[58:61]
	v_mfma_f32_16x16x32_bf16 v[26:29], v[142:145], v[208:211], v[26:29]
	v_mfma_f32_16x16x32_bf16 v[54:57], v[134:137], v[216:219], v[54:57]
	v_mfma_f32_16x16x32_bf16 v[22:25], v[142:145], v[216:219], v[22:25]
	v_mfma_f32_16x16x32_bf16 v[50:53], v[134:137], v[224:227], v[50:53]
	v_mfma_f32_16x16x32_bf16 v[18:21], v[142:145], v[224:227], v[18:21]
	v_mfma_f32_16x16x32_bf16 v[62:65], v[138:141], v[204:207], v[62:65]
	v_mfma_f32_16x16x32_bf16 v[30:33], v[146:149], v[204:207], v[30:33]
	v_mfma_f32_16x16x32_bf16 v[58:61], v[138:141], v[212:215], v[58:61]
	v_mfma_f32_16x16x32_bf16 v[26:29], v[146:149], v[212:215], v[26:29]
	v_mfma_f32_16x16x32_bf16 v[54:57], v[138:141], v[220:223], v[54:57]
	v_mfma_f32_16x16x32_bf16 v[22:25], v[146:149], v[220:223], v[22:25]
	v_mfma_f32_16x16x32_bf16 v[50:53], v[138:141], v[228:231], v[50:53]
	v_mfma_f32_16x16x32_bf16 v[18:21], v[146:149], v[228:231], v[18:21]
	v_mfma_f32_16x16x32_bf16 v[34:37], v[162:165], v[200:203], v[34:37]
	v_mfma_f32_16x16x32_bf16 v[2:5], v[170:173], v[200:203], v[2:5]
	v_mfma_f32_16x16x32_bf16 v[46:49], v[162:165], v[208:211], v[46:49]
	v_mfma_f32_16x16x32_bf16 v[14:17], v[170:173], v[208:211], v[14:17]
	v_mfma_f32_16x16x32_bf16 v[42:45], v[162:165], v[216:219], v[42:45]
	v_mfma_f32_16x16x32_bf16 v[10:13], v[170:173], v[216:219], v[10:13]
	v_mfma_f32_16x16x32_bf16 v[38:41], v[162:165], v[224:227], v[38:41]
	v_mfma_f32_16x16x32_bf16 v[6:9], v[170:173], v[224:227], v[6:9]
	v_mfma_f32_16x16x32_bf16 v[34:37], v[166:169], v[204:207], v[34:37]
	v_mfma_f32_16x16x32_bf16 v[2:5], v[182:185], v[204:207], v[2:5]
	v_mfma_f32_16x16x32_bf16 v[46:49], v[166:169], v[212:215], v[46:49]
	v_mfma_f32_16x16x32_bf16 v[14:17], v[182:185], v[212:215], v[14:17]
	v_mfma_f32_16x16x32_bf16 v[42:45], v[166:169], v[220:223], v[42:45]
	v_mfma_f32_16x16x32_bf16 v[10:13], v[182:185], v[220:223], v[10:13]
	v_mfma_f32_16x16x32_bf16 v[38:41], v[166:169], v[228:231], v[38:41]
	v_mfma_f32_16x16x32_bf16 v[6:9], v[182:185], v[228:231], v[6:9]
	s_setprio 0
	s_barrier
	s_add_i32 s83, s83, 2
	s_add_u32 s75, s75, 0x100
	s_addc_u32 s82, s82, 0
	s_add_u32 s76, s76, 0x100
	s_addc_u32 s77, s77, 0
	s_cmp_gt_u32 s83, 13
	s_cbranch_scc0 .LBB0_856
	s_and_b64 vcc, exec, s[58:59]
	s_cbranch_vccz .LBB0_859
	s_barrier

; #define PG8_STAGE(bufoff, gbase, voff) do { _Pragma("unroll") for (int _i = 0; _i < 2; ++_i) \
;         __builtin_amdgcn_global_load_lds((const unsigned*)((const char*)(gbase) + (voff)[_i]), (PG8_LAS unsigned*)(lds + (bufoff) + ldsw + _i * 8192), 16, 0, 0); } while (0)
; #define PG8_LDA(dst, b, h) do { _Pragma("unroll") for (int m = 0; m < 4; ++m) _Pragma("unroll") for (int k = 0; k < 2; ++k) dst[m][k] = *(const PG8_LAS bf16x8*)(lds + PG8_SA(b, h) + aoff + m * 2048 + k * 1024); } while (0)
; #define PG8_LDB(dst, b, h) do { _Pragma("unroll") for (int n = 0; n < 2; ++n) _Pragma("unroll") for (int k = 0; k < 2; ++k) dst[n][k] = *(const PG8_LAS bf16x8*)(lds + PG8_SB(b, h) + boff + n * 2048 + k * 1024); } while (0)
; #define PG8_MMA(ai, bj, At, Bt) do { __builtin_amdgcn_s_setprio(1); _Pragma("unroll") for (int m = 0; m < 4; ++m) _Pragma("unroll") for (int n = 0; n < 2; ++n) _Pragma("unroll") for (int k = 0; k < 2; ++k) \
;         acc[ai][bj][m][n] = __builtin_amdgcn_mfma_f32_16x16x32_bf16(Bt[n][k], At[m][k], acc[ai][bj][m][n], 0, 0, 0); __builtin_amdgcn_s_setprio(0); } while (0)
; #define PG8_WAIT_V(n) asm volatile("s_waitcnt vmcnt(" #n ")" ::: "memory")
; #define PG8_WAIT_L(n) asm volatile("s_waitcnt lgkmcnt(" #n ")" ::: "memory")
; #define PG8_BAR __builtin_amdgcn_s_barrier()
; #define PG8_SCHED __builtin_amdgcn_sched_barrier(0)
; template <class Epi, class Sched, bool ALIGN_EPI = false, bool SP2 = false>
; __device__ __forceinline__ void gemm_phase(PG8_LAS unsigned char* lds, const Gemm g, const Sched& S, const Epi& E) {
;     ...
;             const bool last = (t == nt - 2);
;             const char* a1 = cA + (size_t)(t + 1) * kstep;
;             const char* a2 = last ? nA : cA + (size_t)(t + 2) * kstep; const char* b2 = last ? nB : cB + (size_t)(t + 2) * kstep;
;             const char* a3 = a2 + kstep; const char* b3 = b2 + kstep;
;             if (last && has_next) S.a_ready(nxt);
;             if constexpr (SP2) {
;             PG8_LDB(B0, 0, 0); PG8_LDB(B1, 0, 1); PG8_SCHED; PG8_LDA(At, 0, 0); PG8_STAGE(PG8_SA(1, 1), a1 + hstep, voffA);
;             PG8_WAIT_V(8); PG8_WAIT_L(0); PG8_BAR; PG8_MMA(0, 0, At, B0); PG8_MMA(0, 1, At, B1); PG8_BAR; PG8_SCHED;
;             PG8_LDA(At, 0, 1); PG8_STAGE(PG8_SB(0, 0), b2, voffB); PG8_STAGE(PG8_SB(0, 1), b2 + hstep, voffB); PG8_STAGE(PG8_SA(0, 0), a2, voffA);
.LBB0_1035:
	s_add_u32 s24, s20, 0x100
	s_addc_u32 s25, s21, 0
	s_add_i32 s64, 0, 0x10000
	s_cmp_eq_u32 s63, 44
	s_cselect_b32 s59, s7, s25
	s_cselect_b32 s58, s6, s24
	v_add_u32_e32 v146, s64, v148
	s_cselect_b32 s27, s19, s62
	s_cselect_b32 s26, s18, s61
	s_add_i32 s65, 0, 0x14000
	ds_read_b128 v[142:145], v146
	ds_read_b128 v[152:155], v146 offset:1024
	ds_read_b128 v[156:159], v146 offset:2048
	ds_read_b128 v[160:163], v146 offset:3072
	v_add_u32_e32 v146, s65, v148
	ds_read_b128 v[164:167], v146
	ds_read_b128 v[168:171], v146 offset:1024
	ds_read_b128 v[172:175], v146 offset:2048
	ds_read_b128 v[180:183], v146 offset:3072
	v_lshl_add_u64 v[146:147], s[20:21], 0, v[140:141]
	s_add_i32 m0, s37, 0xc000
	ds_read_b128 v[184:187], v150
	ds_read_b128 v[200:203], v150 offset:1024
	ds_read_b128 v[204:207], v150 offset:2048
	ds_read_b128 v[208:211], v150 offset:3072
	ds_read_b128 v[212:215], v150 offset:4096
	ds_read_b128 v[216:219], v150 offset:5120
	ds_read_b128 v[220:223], v150 offset:6144
	ds_read_b128 v[224:227], v150 offset:7168
	global_load_lds_dwordx4 v[146:147], off
	v_lshl_add_u64 v[146:147], s[20:21], 0, v[138:139]
	s_add_i32 m0, s37, 0xe000
	s_nop 0
	global_load_lds_dwordx4 v[146:147], off
	s_waitcnt vmcnt(8)
	s_waitcnt lgkmcnt(0)
	s_barrier
	s_setprio 1
	v_mfma_f32_16x16x32_bf16 v[130:133], v[142:145], v[184:187], v[130:133]
	v_mfma_f32_16x16x32_bf16 v[126:129], v[156:159], v[184:187], v[126:129]
	v_mfma_f32_16x16x32_bf16 v[118:121], v[142:145], v[204:207], v[118:121]
	v_mfma_f32_16x16x32_bf16 v[110:113], v[156:159], v[204:207], v[110:113]
	v_mfma_f32_16x16x32_bf16 v[102:105], v[142:145], v[212:215], v[102:105]
	v_mfma_f32_16x16x32_bf16 v[94:97], v[156:159], v[212:215], v[94:97]
	v_mfma_f32_16x16x32_bf16 v[86:89], v[142:145], v[220:223], v[86:89]
	v_mfma_f32_16x16x32_bf16 v[74:77], v[156:159], v[220:223], v[74:77]
	v_mfma_f32_16x16x32_bf16 v[130:133], v[152:155], v[200:203], v[130:133]
	v_mfma_f32_16x16x32_bf16 v[126:129], v[160:163], v[200:203], v[126:129]
	v_mfma_f32_16x16x32_bf16 v[118:121], v[152:155], v[208:211], v[118:121]
	v_mfma_f32_16x16x32_bf16 v[110:113], v[160:163], v[208:211], v[110:113]
	v_mfma_f32_16x16x32_bf16 v[102:105], v[152:155], v[216:219], v[102:105]
	v_mfma_f32_16x16x32_bf16 v[94:97], v[160:163], v[216:219], v[94:97]
	v_mfma_f32_16x16x32_bf16 v[86:89], v[152:155], v[224:227], v[86:89]
	v_mfma_f32_16x16x32_bf16 v[74:77], v[160:163], v[224:227], v[74:77]
	v_mfma_f32_16x16x32_bf16 v[122:125], v[164:167], v[184:187], v[122:125]
	v_mfma_f32_16x16x32_bf16 v[114:117], v[172:175], v[184:187], v[114:117]
	v_mfma_f32_16x16x32_bf16 v[106:109], v[164:167], v[204:207], v[106:109]
	v_mfma_f32_16x16x32_bf16 v[98:101], v[172:175], v[204:207], v[98:101]
	v_mfma_f32_16x16x32_bf16 v[90:93], v[164:167], v[212:215], v[90:93]
	v_mfma_f32_16x16x32_bf16 v[78:81], v[172:175], v[212:215], v[78:81]
	v_mfma_f32_16x16x32_bf16 v[70:73], v[164:167], v[220:223], v[70:73]
	v_mfma_f32_16x16x32_bf16 v[66:69], v[172:175], v[220:223], v[66:69]
	v_mfma_f32_16x16x32_bf16 v[122:125], v[168:171], v[200:203], v[122:125]
	v_mfma_f32_16x16x32_bf16 v[114:117], v[180:183], v[200:203], v[114:117]
	v_mfma_f32_16x16x32_bf16 v[106:109], v[168:171], v[208:211], v[106:109]
	v_mfma_f32_16x16x32_bf16 v[98:101], v[180:183], v[208:211], v[98:101]
	v_mfma_f32_16x16x32_bf16 v[90:93], v[168:171], v[216:219], v[90:93]
	v_mfma_f32_16x16x32_bf16 v[78:81], v[180:183], v[216:219], v[78:81]
	v_mfma_f32_16x16x32_bf16 v[70:73], v[168:171], v[224:227], v[70:73]
	v_mfma_f32_16x16x32_bf16 v[66:69], v[180:183], v[224:227], v[66:69]
	s_setprio 0
	s_barrier
	s_add_i32 s20, s64, s28
	v_lshl_add_u64 v[146:147], s[26:27], 0, v[136:137]
	s_mov_b32 m0, s20
	ds_read_b128 v[184:187], v150 offset:16384
	ds_read_b128 v[200:203], v150 offset:17408
	ds_read_b128 v[204:207], v150 offset:18432
	ds_read_b128 v[208:211], v150 offset:19456
	ds_read_b128 v[212:215], v150 offset:20480
	ds_read_b128 v[216:219], v150 offset:21504
	ds_read_b128 v[220:223], v150 offset:22528
	ds_read_b128 v[224:227], v150 offset:23552
	global_load_lds_dwordx4 v[146:147], off
	s_add_i32 m0, s20, 0x2000
	s_add_u32 s20, s26, 0xc0000
	v_lshl_add_u64 v[176:177], s[26:27], 0, v[134:135]
	s_addc_u32 s21, s27, 0
	s_add_i32 s64, s65, s28
	global_load_lds_dwordx4 v[176:177], off
	v_lshl_add_u64 v[228:229], s[20:21], 0, v[136:137]
	s_mov_b32 m0, s64
	v_lshl_add_u64 v[230:231], s[58:59], 0, v[134:135]
	global_load_lds_dwordx4 v[228:229], off
	v_lshl_add_u64 v[228:229], s[20:21], 0, v[134:135]
	s_add_i32 m0, s64, 0x2000
	s_nop 0
	global_load_lds_dwordx4 v[228:229], off
	v_lshl_add_u64 v[228:229], s[58:59], 0, v[136:137]
	s_mov_b32 m0, s37
	s_nop 0
	global_load_lds_dwordx4 v[228:229], off
	s_mov_b32 m0, s40
	s_nop 0
	global_load_lds_dwordx4 v[230:231], off
	s_waitcnt vmcnt(8)
	s_waitcnt lgkmcnt(0)
	s_barrier
; #define PG8_STAGE(bufoff, gbase, voff) do { _Pragma("unroll") for (int _i = 0; _i < 2; ++_i) \
;         __builtin_amdgcn_global_load_lds((const unsigned*)((const char*)(gbase) + (voff)[_i]), (PG8_LAS unsigned*)(lds + (bufoff) + ldsw + _i * 8192), 16, 0, 0); } while (0)
; #define PG8_LDA(dst, b, h) do { _Pragma("unroll") for (int m = 0; m < 4; ++m) _Pragma("unroll") for (int k = 0; k < 2; ++k) dst[m][k] = *(const PG8_LAS bf16x8*)(lds + PG8_SA(b, h) + aoff + m * 2048 + k * 1024); } while (0)
; #define PG8_LDB(dst, b, h) do { _Pragma("unroll") for (int n = 0; n < 2; ++n) _Pragma("unroll") for (int k = 0; k < 2; ++k) dst[n][k] = *(const PG8_LAS bf16x8*)(lds + PG8_SB(b, h) + boff + n * 2048 + k * 1024); } while (0)
; #define PG8_MMA(ai, bj, At, Bt) do { __builtin_amdgcn_s_setprio(1); _Pragma("unroll") for (int m = 0; m < 4; ++m) _Pragma("unroll") for (int n = 0; n < 2; ++n) _Pragma("unroll") for (int k = 0; k < 2; ++k) \
;         acc[ai][bj][m][n] = __builtin_amdgcn_mfma_f32_16x16x32_bf16(Bt[n][k], At[m][k], acc[ai][bj][m][n], 0, 0, 0); __builtin_amdgcn_s_setprio(0); } while (0)
; #define PG8_WAIT_V(n) asm volatile("s_waitcnt vmcnt(" #n ")" ::: "memory")
; #define PG8_WAIT_L(n) asm volatile("s_waitcnt lgkmcnt(" #n ")" ::: "memory")
; #define PG8_BAR __builtin_amdgcn_s_barrier()
; #define PG8_SCHED __builtin_amdgcn_sched_barrier(0)
; template <class Epi, class Sched, bool ALIGN_EPI = false, bool SP2 = false>
; __device__ __forceinline__ void gemm_phase(PG8_LAS unsigned char* lds, const Gemm g, const Sched& S, const Epi& E) {
;     ...
;             PG8_WAIT_V(8); PG8_WAIT_L(0); PG8_BAR; PG8_MMA(1, 0, At, B0); PG8_MMA(1, 1, At, B1); PG8_BAR; PG8_SCHED;
;             PG8_LDB(B0, 1, 0); PG8_LDB(B1, 1, 1); PG8_SCHED; PG8_LDA(At, 1, 0); PG8_STAGE(PG8_SA(0, 1), a2 + hstep, voffA);
;             PG8_WAIT_V(8); PG8_WAIT_L(0); PG8_BAR; PG8_MMA(0, 0, At, B0); PG8_MMA(0, 1, At, B1); PG8_BAR; PG8_SCHED;
	s_setprio 1
	v_mfma_f32_16x16x32_bf16 v[62:65], v[142:145], v[184:187], v[62:65]
	v_mfma_f32_16x16x32_bf16 v[58:61], v[156:159], v[184:187], v[58:61]
	v_mfma_f32_16x16x32_bf16 v[50:53], v[142:145], v[204:207], v[50:53]
	v_mfma_f32_16x16x32_bf16 v[42:45], v[156:159], v[204:207], v[42:45]
	v_mfma_f32_16x16x32_bf16 v[34:37], v[142:145], v[212:215], v[34:37]
	v_mfma_f32_16x16x32_bf16 v[26:29], v[156:159], v[212:215], v[26:29]
	v_mfma_f32_16x16x32_bf16 v[18:21], v[142:145], v[220:223], v[18:21]
	v_mfma_f32_16x16x32_bf16 v[10:13], v[156:159], v[220:223], v[10:13]
	v_mfma_f32_16x16x32_bf16 v[62:65], v[152:155], v[200:203], v[62:65]
	v_mfma_f32_16x16x32_bf16 v[58:61], v[160:163], v[200:203], v[58:61]
	v_mfma_f32_16x16x32_bf16 v[50:53], v[152:155], v[208:211], v[50:53]
	v_mfma_f32_16x16x32_bf16 v[42:45], v[160:163], v[208:211], v[42:45]
	v_mfma_f32_16x16x32_bf16 v[34:37], v[152:155], v[216:219], v[34:37]
	v_mfma_f32_16x16x32_bf16 v[26:29], v[160:163], v[216:219], v[26:29]
	v_mfma_f32_16x16x32_bf16 v[18:21], v[152:155], v[224:227], v[18:21]
	v_mfma_f32_16x16x32_bf16 v[10:13], v[160:163], v[224:227], v[10:13]
	v_mfma_f32_16x16x32_bf16 v[54:57], v[164:167], v[184:187], v[54:57]
	v_mfma_f32_16x16x32_bf16 v[46:49], v[172:175], v[184:187], v[46:49]
	v_mfma_f32_16x16x32_bf16 v[38:41], v[164:167], v[204:207], v[38:41]
	v_mfma_f32_16x16x32_bf16 v[30:33], v[172:175], v[204:207], v[30:33]
	v_mfma_f32_16x16x32_bf16 v[22:25], v[164:167], v[212:215], v[22:25]
	v_mfma_f32_16x16x32_bf16 v[14:17], v[172:175], v[212:215], v[14:17]
	v_mfma_f32_16x16x32_bf16 v[6:9], v[164:167], v[220:223], v[6:9]
	v_mfma_f32_16x16x32_bf16 v[2:5], v[172:175], v[220:223], v[2:5]
	v_mfma_f32_16x16x32_bf16 v[54:57], v[168:171], v[200:203], v[54:57]
	v_mfma_f32_16x16x32_bf16 v[46:49], v[180:183], v[200:203], v[46:49]
	v_mfma_f32_16x16x32_bf16 v[38:41], v[168:171], v[208:211], v[38:41]
	v_mfma_f32_16x16x32_bf16 v[30:33], v[180:183], v[208:211], v[30:33]
	v_mfma_f32_16x16x32_bf16 v[22:25], v[168:171], v[216:219], v[22:25]
	v_mfma_f32_16x16x32_bf16 v[14:17], v[180:183], v[216:219], v[14:17]
	v_mfma_f32_16x16x32_bf16 v[6:9], v[168:171], v[224:227], v[6:9]
	v_mfma_f32_16x16x32_bf16 v[2:5], v[180:183], v[224:227], v[2:5]
	s_setprio 0
	s_barrier
	s_add_i32 s64, 0, 0x18000
	v_add_u32_e32 v151, s64, v148
	s_add_i32 s65, 0, 0x1c000
	ds_read_b128 v[142:145], v151
	ds_read_b128 v[152:155], v151 offset:1024
	ds_read_b128 v[156:159], v151 offset:2048
	ds_read_b128 v[160:163], v151 offset:3072
	v_add_u32_e32 v151, s65, v148
	ds_read_b128 v[164:167], v151
	ds_read_b128 v[168:171], v151 offset:1024
	ds_read_b128 v[172:175], v151 offset:2048
	ds_read_b128 v[180:183], v151 offset:3072
	s_add_u32 s20, s58, 0xc0000
	s_addc_u32 s21, s59, 0
	s_mov_b32 m0, s41
	v_lshl_add_u64 v[232:233], s[20:21], 0, v[136:137]
	ds_read_b128 v[184:187], v150 offset:32768
	ds_read_b128 v[200:203], v150 offset:33792
	ds_read_b128 v[204:207], v150 offset:34816
	ds_read_b128 v[208:211], v150 offset:35840
	ds_read_b128 v[212:215], v150 offset:36864
	ds_read_b128 v[216:219], v150 offset:37888
	ds_read_b128 v[220:223], v150 offset:38912
	ds_read_b128 v[224:227], v150 offset:39936
	global_load_lds_dwordx4 v[232:233], off
	v_lshl_add_u64 v[232:233], s[20:21], 0, v[134:135]
	s_mov_b32 m0, s42
	s_nop 0
	global_load_lds_dwordx4 v[232:233], off
	s_waitcnt vmcnt(8)
	s_waitcnt lgkmcnt(0)
	s_barrier
	s_setprio 1
	v_mfma_f32_16x16x32_bf16 v[130:133], v[142:145], v[184:187], v[130:133]
	v_mfma_f32_16x16x32_bf16 v[126:129], v[156:159], v[184:187], v[126:129]
	v_mfma_f32_16x16x32_bf16 v[118:121], v[142:145], v[204:207], v[118:121]
	v_mfma_f32_16x16x32_bf16 v[110:113], v[156:159], v[204:207], v[110:113]
	v_mfma_f32_16x16x32_bf16 v[102:105], v[142:145], v[212:215], v[102:105]
	v_mfma_f32_16x16x32_bf16 v[94:97], v[156:159], v[212:215], v[94:97]
	v_mfma_f32_16x16x32_bf16 v[86:89], v[142:145], v[220:223], v[86:89]
	v_mfma_f32_16x16x32_bf16 v[74:77], v[156:159], v[220:223], v[74:77]
	v_mfma_f32_16x16x32_bf16 v[130:133], v[152:155], v[200:203], v[130:133]
	v_mfma_f32_16x16x32_bf16 v[126:129], v[160:163], v[200:203], v[126:129]
	v_mfma_f32_16x16x32_bf16 v[118:121], v[152:155], v[208:211], v[118:121]
	v_mfma_f32_16x16x32_bf16 v[110:113], v[160:163], v[208:211], v[110:113]
	v_mfma_f32_16x16x32_bf16 v[102:105], v[152:155], v[216:219], v[102:105]
	v_mfma_f32_16x16x32_bf16 v[94:97], v[160:163], v[216:219], v[94:97]
	v_mfma_f32_16x16x32_bf16 v[86:89], v[152:155], v[224:227], v[86:89]
	v_mfma_f32_16x16x32_bf16 v[74:77], v[160:163], v[224:227], v[74:77]
	v_mfma_f32_16x16x32_bf16 v[122:125], v[164:167], v[184:187], v[122:125]
	v_mfma_f32_16x16x32_bf16 v[114:117], v[172:175], v[184:187], v[114:117]
	v_mfma_f32_16x16x32_bf16 v[106:109], v[164:167], v[204:207], v[106:109]
	v_mfma_f32_16x16x32_bf16 v[98:101], v[172:175], v[204:207], v[98:101]
	v_mfma_f32_16x16x32_bf16 v[90:93], v[164:167], v[212:215], v[90:93]
	v_mfma_f32_16x16x32_bf16 v[78:81], v[172:175], v[212:215], v[78:81]
	v_mfma_f32_16x16x32_bf16 v[70:73], v[164:167], v[220:223], v[70:73]
	v_mfma_f32_16x16x32_bf16 v[66:69], v[172:175], v[220:223], v[66:69]
	v_mfma_f32_16x16x32_bf16 v[122:125], v[168:171], v[200:203], v[122:125]
	v_mfma_f32_16x16x32_bf16 v[114:117], v[180:183], v[200:203], v[114:117]
	v_mfma_f32_16x16x32_bf16 v[106:109], v[168:171], v[208:211], v[106:109]
	v_mfma_f32_16x16x32_bf16 v[98:101], v[180:183], v[208:211], v[98:101]
	v_mfma_f32_16x16x32_bf16 v[90:93], v[168:171], v[216:219], v[90:93]
	v_mfma_f32_16x16x32_bf16 v[78:81], v[180:183], v[216:219], v[78:81]
	v_mfma_f32_16x16x32_bf16 v[70:73], v[168:171], v[224:227], v[70:73]
	v_mfma_f32_16x16x32_bf16 v[66:69], v[180:183], v[224:227], v[66:69]
	s_setprio 0
	s_barrier
; #define PG8_STAGE(bufoff, gbase, voff) do { _Pragma("unroll") for (int _i = 0; _i < 2; ++_i) \
;         __builtin_amdgcn_global_load_lds((const unsigned*)((const char*)(gbase) + (voff)[_i]), (PG8_LAS unsigned*)(lds + (bufoff) + ldsw + _i * 8192), 16, 0, 0); } while (0)
; #define PG8_LDA(dst, b, h) do { _Pragma("unroll") for (int m = 0; m < 4; ++m) _Pragma("unroll") for (int k = 0; k < 2; ++k) dst[m][k] = *(const PG8_LAS bf16x8*)(lds + PG8_SA(b, h) + aoff + m * 2048 + k * 1024); } while (0)
; #define PG8_MMA(ai, bj, At, Bt) do { __builtin_amdgcn_s_setprio(1); _Pragma("unroll") for (int m = 0; m < 4; ++m) _Pragma("unroll") for (int n = 0; n < 2; ++n) _Pragma("unroll") for (int k = 0; k < 2; ++k) \
;         acc[ai][bj][m][n] = __builtin_amdgcn_mfma_f32_16x16x32_bf16(Bt[n][k], At[m][k], acc[ai][bj][m][n], 0, 0, 0); __builtin_amdgcn_s_setprio(0); } while (0)
; #define PG8_WAIT_V(n) asm volatile("s_waitcnt vmcnt(" #n ")" ::: "memory")
; #define PG8_WAIT_L(n) asm volatile("s_waitcnt lgkmcnt(" #n ")" ::: "memory")
; #define PG8_BAR __builtin_amdgcn_s_barrier()
; #define PG8_SCHED __builtin_amdgcn_sched_barrier(0)
; template <class Epi, class Sched, bool ALIGN_EPI = false, bool SP2 = false>
; __device__ __forceinline__ void gemm_phase(PG8_LAS unsigned char* lds, const Gemm g, const Sched& S, const Epi& E) {
;     ...
;         for (int t = 0; t < nt; t += 2) {
;             const bool last = (t == nt - 2);
;             const char* a1 = cA + (size_t)(t + 1) * kstep;
;             const char* a2 = last ? nA : cA + (size_t)(t + 2) * kstep; const char* b2 = last ? nB : cB + (size_t)(t + 2) * kstep;
;     ...
;             PG8_LDA(At, 1, 1); PG8_STAGE(PG8_SB(1, 0), b3, voffB); PG8_STAGE(PG8_SB(1, 1), b3 + hstep, voffB); PG8_STAGE(PG8_SA(1, 0), a3, voffA);
;             PG8_WAIT_V(8); PG8_WAIT_L(0); PG8_BAR; PG8_MMA(1, 0, At, B0); PG8_MMA(1, 1, At, B1); PG8_BAR; PG8_SCHED;
	s_add_i32 s20, s64, s28
	v_lshl_add_u64 v[146:147], v[146:147], 0, s[38:39]
	s_mov_b32 m0, s20
	ds_read_b128 v[184:187], v150 offset:49152
	ds_read_b128 v[200:203], v150 offset:50176
	ds_read_b128 v[204:207], v150 offset:51200
	ds_read_b128 v[208:211], v150 offset:52224
	ds_read_b128 v[212:215], v150 offset:53248
	ds_read_b128 v[216:219], v150 offset:54272
	ds_read_b128 v[220:223], v150 offset:55296
	ds_read_b128 v[224:227], v150 offset:56320
	global_load_lds_dwordx4 v[146:147], off
	s_add_i32 m0, s20, 0x2000
	s_add_u32 s20, s26, 0xc0080
	v_lshl_add_u64 v[146:147], v[176:177], 0, s[38:39]
	s_addc_u32 s21, s27, 0
	s_add_i32 s26, s65, s28
	global_load_lds_dwordx4 v[146:147], off
	v_lshl_add_u64 v[146:147], s[20:21], 0, v[136:137]
	s_mov_b32 m0, s26
	s_nop 0
	global_load_lds_dwordx4 v[146:147], off
	v_lshl_add_u64 v[146:147], s[20:21], 0, v[134:135]
	s_add_i32 m0, s26, 0x2000
	s_nop 0
	global_load_lds_dwordx4 v[146:147], off
	v_lshl_add_u64 v[146:147], v[228:229], 0, s[38:39]
	s_mov_b32 m0, s49
	s_nop 0
	global_load_lds_dwordx4 v[146:147], off
	v_lshl_add_u64 v[146:147], v[230:231], 0, s[38:39]
	s_mov_b32 m0, s52
	s_nop 0
	global_load_lds_dwordx4 v[146:147], off
	s_waitcnt vmcnt(8)
	s_waitcnt lgkmcnt(0)
	s_barrier
	s_setprio 1
	v_mfma_f32_16x16x32_bf16 v[62:65], v[142:145], v[184:187], v[62:65]
	v_mfma_f32_16x16x32_bf16 v[58:61], v[156:159], v[184:187], v[58:61]
	v_mfma_f32_16x16x32_bf16 v[50:53], v[142:145], v[204:207], v[50:53]
	v_mfma_f32_16x16x32_bf16 v[42:45], v[156:159], v[204:207], v[42:45]
	v_mfma_f32_16x16x32_bf16 v[34:37], v[142:145], v[212:215], v[34:37]
	v_mfma_f32_16x16x32_bf16 v[26:29], v[156:159], v[212:215], v[26:29]
	v_mfma_f32_16x16x32_bf16 v[18:21], v[142:145], v[220:223], v[18:21]
	v_mfma_f32_16x16x32_bf16 v[10:13], v[156:159], v[220:223], v[10:13]
	v_mfma_f32_16x16x32_bf16 v[62:65], v[152:155], v[200:203], v[62:65]
	v_mfma_f32_16x16x32_bf16 v[58:61], v[160:163], v[200:203], v[58:61]
	v_mfma_f32_16x16x32_bf16 v[50:53], v[152:155], v[208:211], v[50:53]
	v_mfma_f32_16x16x32_bf16 v[42:45], v[160:163], v[208:211], v[42:45]
	v_mfma_f32_16x16x32_bf16 v[34:37], v[152:155], v[216:219], v[34:37]
	v_mfma_f32_16x16x32_bf16 v[26:29], v[160:163], v[216:219], v[26:29]
	v_mfma_f32_16x16x32_bf16 v[18:21], v[152:155], v[224:227], v[18:21]
	v_mfma_f32_16x16x32_bf16 v[10:13], v[160:163], v[224:227], v[10:13]
	v_mfma_f32_16x16x32_bf16 v[54:57], v[164:167], v[184:187], v[54:57]
	v_mfma_f32_16x16x32_bf16 v[46:49], v[172:175], v[184:187], v[46:49]
	v_mfma_f32_16x16x32_bf16 v[38:41], v[164:167], v[204:207], v[38:41]
	v_mfma_f32_16x16x32_bf16 v[30:33], v[172:175], v[204:207], v[30:33]
	v_mfma_f32_16x16x32_bf16 v[22:25], v[164:167], v[212:215], v[22:25]
	v_mfma_f32_16x16x32_bf16 v[14:17], v[172:175], v[212:215], v[14:17]
	v_mfma_f32_16x16x32_bf16 v[6:9], v[164:167], v[220:223], v[6:9]
	v_mfma_f32_16x16x32_bf16 v[2:5], v[172:175], v[220:223], v[2:5]
	v_mfma_f32_16x16x32_bf16 v[54:57], v[168:171], v[200:203], v[54:57]
	v_mfma_f32_16x16x32_bf16 v[46:49], v[180:183], v[200:203], v[46:49]
	v_mfma_f32_16x16x32_bf16 v[38:41], v[168:171], v[208:211], v[38:41]
	v_mfma_f32_16x16x32_bf16 v[30:33], v[180:183], v[208:211], v[30:33]
	v_mfma_f32_16x16x32_bf16 v[22:25], v[168:171], v[216:219], v[22:25]
	v_mfma_f32_16x16x32_bf16 v[14:17], v[180:183], v[216:219], v[14:17]
	v_mfma_f32_16x16x32_bf16 v[6:9], v[168:171], v[224:227], v[6:9]
	v_mfma_f32_16x16x32_bf16 v[2:5], v[180:183], v[224:227], v[2:5]
	s_setprio 0
	s_barrier
	s_add_i32 s63, s63, 2
	s_add_u32 s61, s61, 0x100
	s_addc_u32 s62, s62, 0
	s_cmp_gt_u32 s63, 45
	s_mov_b64 s[20:21], s[24:25]
	s_cbranch_scc0 .LBB0_1035
	s_and_b64 vcc, exec, s[16:17]
	s_cbranch_vccz .LBB0_1038
	s_barrier
